# attention loop: V group-0 fragment reads of tile t+1 issued behind tile t's last PV group; PV(0,0) no longer waits for the K reads (counted lgkmcnt per QK MFMA)
# baseline (speedup 1.0000x reference)
; #define SBAR() __builtin_amdgcn_sched_barrier(0)
; template <int KS> __device__ __forceinline__ void pv_ks(f32x16* o, int vb, bf16x8 pa) {
;     const s16x4 l0 = tr_read<v_rd_off(0, KS, 0)>(vb), h0 = tr_read<v_rd_off(0, KS, 1)>(vb), l1 = tr_read<v_rd_off(1, KS, 0)>(vb), h1 = tr_read<v_rd_off(1, KS, 1)>(vb);
;     const s16x4 l2 = tr_read<v_rd_off(2, KS, 0)>(vb), h2 = tr_read<v_rd_off(2, KS, 1)>(vb), l3 = tr_read<v_rd_off(3, KS, 0)>(vb), h3 = tr_read<v_rd_off(3, KS, 1)>(vb);
;     ...
;     asm volatile("s_waitcnt lgkmcnt(6)" ::: "memory"); SBAR();
.Lsym_biasdone_n:
	s_add_i32 s55, s55, 64
	v_add_f32_e32 v183, 0xc2800000, v183
	ds_read_b64_tr_b16 v[144:145], v252 offset:0
	ds_read_b64_tr_b16 v[146:147], v252 offset:2048
	ds_read_b64_tr_b16 v[148:149], v252 offset:512
	ds_read_b64_tr_b16 v[150:151], v252 offset:2560
	ds_read_b64_tr_b16 v[152:153], v252 offset:1024
	ds_read_b64_tr_b16 v[154:155], v252 offset:3072
	ds_read_b64_tr_b16 v[156:157], v252 offset:1536
	ds_read_b64_tr_b16 v[158:159], v252 offset:3584

; #define SBAR() __builtin_amdgcn_sched_barrier(0)
; #define PK4(P, BASE, OUT) do { u32x4 w = {cvtpk(P[BASE + 0], P[BASE + 1]), cvtpk(P[BASE + 2], P[BASE + 3]), cvtpk(P[BASE + 4], P[BASE + 5]), cvtpk(P[BASE + 6], P[BASE + 7])}; \
;     OUT = *reinterpret_cast<bf16x8*>(&w); } while (0)
; template <int KS> __device__ __forceinline__ void pv_ks(f32x16* o, int vb, bf16x8 pa) {
;     const s16x4 l0 = tr_read<v_rd_off(0, KS, 0)>(vb), h0 = tr_read<v_rd_off(0, KS, 1)>(vb), l1 = tr_read<v_rd_off(1, KS, 0)>(vb), h1 = tr_read<v_rd_off(1, KS, 1)>(vb);
;     const s16x4 l2 = tr_read<v_rd_off(2, KS, 0)>(vb), h2 = tr_read<v_rd_off(2, KS, 1)>(vb), l3 = tr_read<v_rd_off(3, KS, 0)>(vb), h3 = tr_read<v_rd_off(3, KS, 1)>(vb);
;     ...
;     asm volatile("s_waitcnt lgkmcnt(6)" ::: "memory"); SBAR();
;     o[0] = __builtin_amdgcn_mfma_f32_32x32x16_bf16(pa, PK(l0, h0), o[0], 0, 0, 0);
;     asm volatile("s_waitcnt lgkmcnt(4)" ::: "memory"); SBAR();
;     o[1] = __builtin_amdgcn_mfma_f32_32x32x16_bf16(pa, PK(l1, h1), o[1], 0, 0, 0);
;     asm volatile("s_waitcnt lgkmcnt(2)" ::: "memory"); SBAR();
;     o[2] = __builtin_amdgcn_mfma_f32_32x32x16_bf16(pa, PK(l2, h2), o[2], 0, 0, 0);
;     asm volatile("s_waitcnt lgkmcnt(0)" ::: "memory"); SBAR();
;     o[3] = __builtin_amdgcn_mfma_f32_32x32x16_bf16(pa, PK(l3, h3), o[3], 0, 0, 0);
;     ...
; }
; __device__ __forceinline__ void pv_d0(f32x16* o, int vb, bf16x8 pa0, bf16x8 pa1, bf16x8 pa2, bf16x8 pa3) {
;     __builtin_amdgcn_s_setprio(1);
;     pv_ks<0>(o, vb, pa0); pv_ks<1>(o, vb, pa1); pv_ks<2>(o, vb, pa2); pv_ks<3>(o, vb, pa3);
;     __builtin_amdgcn_s_setprio(0);
; }
; __device__ __forceinline__ void exp_half(f32x16& p) {
; #pragma unroll
;     for (int r = 0; r < 16; ++r) p[r] = __builtin_amdgcn_exp2f(p[r]);
; }
; __device__ __forceinline__ void pack_p(const f32x16& p0, const f32x16& p1, float& l_reg, bf16x8& pa0, bf16x8& pa1, bf16x8& pa2, bf16x8& pa3) {
;     float ps = 0;
; #pragma unroll
;     for (int r = 0; r < 16; ++r) ps += p0[r];
; #pragma unroll
;     for (int r = 0; r < 16; ++r) ps += p1[r];
;     l_reg += ps;
;     ...
;     PK4(p0, 0, pa0); PK4(p0, 8, pa1); PK4(p1, 0, pa2); PK4(p1, 8, pa3);
;     ...
; }
.Lsym_nostage_s0:
	s_waitcnt lgkmcnt(14)
	v_mfma_f32_32x32x16_bf16 v[48:63], v[128:131], v[144:147], v[48:63]
	ds_read_b64_tr_b16 v[144:145], v252 offset:4096
	ds_read_b64_tr_b16 v[146:147], v252 offset:6144
	v_exp_f32_e32 v88, v88
	v_exp_f32_e32 v89, v89
	v_exp_f32_e32 v90, v90
	v_exp_f32_e32 v91, v91
	v_add_f32_e32 v182, v88, v182
	s_waitcnt lgkmcnt(9)
	v_mfma_f32_32x32x16_bf16 v[112:127], v[192:195], v[172:175], v[112:127]
	v_add_f32_e32 v182, v89, v182
	v_cvt_pk_bf16_f32 v132, v88, v89
	v_exp_f32_e32 v92, v92
	v_exp_f32_e32 v93, v93
	v_mfma_f32_32x32x16_bf16 v[32:47], v[128:131], v[148:151], v[32:47]
	ds_read_b64_tr_b16 v[148:149], v252 offset:4608
	ds_read_b64_tr_b16 v[150:151], v252 offset:6656
	v_add_f32_e32 v182, v90, v182
	v_add_f32_e32 v182, v91, v182
	v_cvt_pk_bf16_f32 v133, v90, v91
	v_exp_f32_e32 v94, v94
	v_exp_f32_e32 v95, v95
	s_waitcnt lgkmcnt(10)
	v_mfma_f32_32x32x16_bf16 v[96:111], v[196:199], v[172:175], v[96:111]
	v_add_f32_e32 v182, v92, v182
	v_add_f32_e32 v182, v93, v182
	v_cvt_pk_bf16_f32 v134, v92, v93
	v_cvt_pk_bf16_f32 v135, v94, v95
	v_mfma_f32_32x32x16_bf16 v[16:31], v[128:131], v[152:155], v[16:31]
	ds_read_b64_tr_b16 v[152:153], v252 offset:5120
	ds_read_b64_tr_b16 v[154:155], v252 offset:7168
	v_add_f32_e32 v182, v94, v182
	v_add_f32_e32 v182, v95, v182
	v_exp_f32_e32 v64, v64
	v_exp_f32_e32 v65, v65
	v_exp_f32_e32 v66, v66
	s_waitcnt lgkmcnt(11)
	v_mfma_f32_32x32x16_bf16 v[112:127], v[200:203], v[168:171], v[112:127]
	v_exp_f32_e32 v67, v67
	v_add_f32_e32 v182, v64, v182
	v_add_f32_e32 v182, v65, v182
	v_cvt_pk_bf16_f32 v136, v64, v65
	v_mfma_f32_32x32x16_bf16 v[0:15], v[128:131], v[156:159], v[0:15]
	ds_read_b64_tr_b16 v[156:157], v252 offset:5632
	ds_read_b64_tr_b16 v[158:159], v252 offset:7680
	v_exp_f32_e32 v68, v68
	v_exp_f32_e32 v69, v69
	v_add_f32_e32 v182, v66, v182
	v_add_f32_e32 v182, v67, v182
	v_cvt_pk_bf16_f32 v137, v66, v67
	s_waitcnt lgkmcnt(12)
	v_mfma_f32_32x32x16_bf16 v[96:111], v[204:207], v[168:171], v[96:111]
	v_exp_f32_e32 v70, v70
	v_exp_f32_e32 v71, v71
	v_add_f32_e32 v182, v68, v182
	v_add_f32_e32 v182, v69, v182
	s_waitcnt lgkmcnt(6)
	v_mfma_f32_32x32x16_bf16 v[48:63], v[132:135], v[144:147], v[48:63]
	ds_read_b64_tr_b16 v[144:145], v252 offset:8192
	ds_read_b64_tr_b16 v[146:147], v252 offset:10240
	v_cvt_pk_bf16_f32 v138, v68, v69
	v_cvt_pk_bf16_f32 v139, v70, v71
	v_add_f32_e32 v182, v70, v182
	v_add_f32_e32 v182, v71, v182
	v_exp_f32_e32 v72, v72
	v_mfma_f32_32x32x16_bf16 v[112:127], v[208:211], v[164:167], v[112:127]
	v_exp_f32_e32 v73, v73
	v_exp_f32_e32 v74, v74
	v_exp_f32_e32 v75, v75
	v_add_f32_e32 v182, v72, v182
	v_add_f32_e32 v182, v73, v182
	s_waitcnt lgkmcnt(6)
	v_mfma_f32_32x32x16_bf16 v[32:47], v[132:135], v[148:151], v[32:47]
	ds_read_b64_tr_b16 v[148:149], v252 offset:8704
	ds_read_b64_tr_b16 v[150:151], v252 offset:10752
	v_cvt_pk_bf16_f32 v140, v72, v73
	v_exp_f32_e32 v76, v76
	v_exp_f32_e32 v77, v77
	v_add_f32_e32 v182, v74, v182
	v_add_f32_e32 v182, v75, v182
	v_mfma_f32_32x32x16_bf16 v[96:111], v[212:215], v[164:167], v[96:111]
	v_cvt_pk_bf16_f32 v141, v74, v75
	v_exp_f32_e32 v78, v78
	v_exp_f32_e32 v79, v79
	v_add_f32_e32 v182, v76, v182
	v_add_f32_e32 v182, v77, v182
	s_waitcnt lgkmcnt(6)
	v_mfma_f32_32x32x16_bf16 v[16:31], v[132:135], v[152:155], v[16:31]
	ds_read_b64_tr_b16 v[152:153], v252 offset:9216
	ds_read_b64_tr_b16 v[154:155], v252 offset:11264
	v_cvt_pk_bf16_f32 v142, v76, v77
	v_cvt_pk_bf16_f32 v143, v78, v79
	v_add_f32_e32 v182, v78, v182
	v_add_f32_e32 v182, v79, v182
	s_cmp_lt_i32 s55, 0
	v_mfma_f32_32x32x16_bf16 v[112:127], v[216:219], v[160:163], v[112:127]
	s_cselect_b32 s100, -1.0, 1.0
	v_mul_f32_e32 v185, s100, v186
	v_fma_f32 v187, -v185, v183, s16
	v_fmamk_f32 v80, v185, 0x00000000, v187
	v_fmamk_f32 v81, v185, 0x3f800000, v187
	s_waitcnt lgkmcnt(6)
	v_mfma_f32_32x32x16_bf16 v[0:15], v[132:135], v[156:159], v[0:15]
	ds_read_b64_tr_b16 v[156:157], v252 offset:9728
	ds_read_b64_tr_b16 v[158:159], v252 offset:11776
	v_fmamk_f32 v82, v185, 0x40000000, v187
	v_fmamk_f32 v83, v185, 0x40400000, v187
	v_fmamk_f32 v84, v185, 0x41000000, v187
	v_fmamk_f32 v85, v185, 0x41100000, v187
	v_fmamk_f32 v86, v185, 0x41200000, v187
	v_mfma_f32_32x32x16_bf16 v[96:111], v[220:223], v[160:163], v[96:111]
	v_fmamk_f32 v87, v185, 0x41300000, v187
	v_fmamk_f32 v88, v185, 0x41800000, v187
	v_fmamk_f32 v89, v185, 0x41880000, v187
	v_fmamk_f32 v90, v185, 0x41900000, v187
	v_fmamk_f32 v91, v185, 0x41980000, v187
	s_waitcnt lgkmcnt(6)
	v_mfma_f32_32x32x16_bf16 v[48:63], v[136:139], v[144:147], v[48:63]
	ds_read_b64_tr_b16 v[144:145], v252 offset:12288
	ds_read_b64_tr_b16 v[146:147], v252 offset:14336
	v_fmamk_f32 v92, v185, 0x41c00000, v187
	v_fmamk_f32 v93, v185, 0x41c80000, v187
	v_fmamk_f32 v94, v185, 0x41d00000, v187
	v_fmamk_f32 v95, v185, 0x41d80000, v187
	v_fmamk_f32 v64, v185, 0x42000000, v187
	s_waitcnt lgkmcnt(6)
; #define SBAR() __builtin_amdgcn_sched_barrier(0)
; template <int KS> __device__ __forceinline__ void pv_ks(f32x16* o, int vb, bf16x8 pa) {
;     const s16x4 l0 = tr_read<v_rd_off(0, KS, 0)>(vb), h0 = tr_read<v_rd_off(0, KS, 1)>(vb), l1 = tr_read<v_rd_off(1, KS, 0)>(vb), h1 = tr_read<v_rd_off(1, KS, 1)>(vb);
;     const s16x4 l2 = tr_read<v_rd_off(2, KS, 0)>(vb), h2 = tr_read<v_rd_off(2, KS, 1)>(vb), l3 = tr_read<v_rd_off(3, KS, 0)>(vb), h3 = tr_read<v_rd_off(3, KS, 1)>(vb);
;     ...
;     asm volatile("s_waitcnt lgkmcnt(6)" ::: "memory"); SBAR();
;     o[0] = __builtin_amdgcn_mfma_f32_32x32x16_bf16(pa, PK(l0, h0), o[0], 0, 0, 0);
;     asm volatile("s_waitcnt lgkmcnt(4)" ::: "memory"); SBAR();
;     o[1] = __builtin_amdgcn_mfma_f32_32x32x16_bf16(pa, PK(l1, h1), o[1], 0, 0, 0);
;     asm volatile("s_waitcnt lgkmcnt(2)" ::: "memory"); SBAR();
;     o[2] = __builtin_amdgcn_mfma_f32_32x32x16_bf16(pa, PK(l2, h2), o[2], 0, 0, 0);
;     asm volatile("s_waitcnt lgkmcnt(0)" ::: "memory"); SBAR();
;     o[3] = __builtin_amdgcn_mfma_f32_32x32x16_bf16(pa, PK(l3, h3), o[3], 0, 0, 0);
;     ...
; }
; __device__ __forceinline__ void pv_d0(f32x16* o, int vb, bf16x8 pa0, bf16x8 pa1, bf16x8 pa2, bf16x8 pa3) {
;     __builtin_amdgcn_s_setprio(1);
;     pv_ks<0>(o, vb, pa0); pv_ks<1>(o, vb, pa1); pv_ks<2>(o, vb, pa2); pv_ks<3>(o, vb, pa3);
;     __builtin_amdgcn_s_setprio(0);
; }
; __device__ __forceinline__ void exp_half(f32x16& p) {
; #pragma unroll
;     for (int r = 0; r < 16; ++r) p[r] = __builtin_amdgcn_exp2f(p[r]);
; }
; __device__ __forceinline__ void pack_p(const f32x16& p0, const f32x16& p1, float& l_reg, bf16x8& pa0, bf16x8& pa1, bf16x8& pa2, bf16x8& pa3) {
;     float ps = 0;
; #pragma unroll
;     for (int r = 0; r < 16; ++r) ps += p0[r];
; #pragma unroll
;     for (int r = 0; r < 16; ++r) ps += p1[r];
;     l_reg += ps;
;     ...
;     PK4(p0, 0, pa0); PK4(p0, 8, pa1); PK4(p1, 0, pa2); PK4(p1, 8, pa3);
;     ...
; }
; __device__ __forceinline__ void bias_init(f32x16& p0, f32x16& p1, float base, float nslope2, float nM2, int rel  ) {
;     if (rel <= -63 || rel >= 31) {
;         const float sg = (rel < 0) ? -nslope2 : nslope2, lbv = fmaf(-sg, base, nM2);
; #pragma unroll
;         for (int r = 0; r < 16; ++r) { p0[r] = fmaf((float)((r & 3) + 8 * (r >> 2)), sg, lbv); p1[r] = fmaf((float)((r & 3) + 8 * (r >> 2) + 32), sg, lbv); }
;     } else {
; #pragma unroll
	v_mfma_f32_32x32x16_bf16 v[32:47], v[136:139], v[148:151], v[32:47]
	ds_read_b64_tr_b16 v[148:149], v252 offset:12800
	ds_read_b64_tr_b16 v[150:151], v252 offset:14848
	v_fmamk_f32 v65, v185, 0x42040000, v187
	v_fmamk_f32 v66, v185, 0x42080000, v187
	v_fmamk_f32 v67, v185, 0x420c0000, v187
	v_fmamk_f32 v68, v185, 0x42200000, v187
	v_fmamk_f32 v69, v185, 0x42240000, v187
	s_waitcnt lgkmcnt(6)
	v_mfma_f32_32x32x16_bf16 v[16:31], v[136:139], v[152:155], v[16:31]
	ds_read_b64_tr_b16 v[152:153], v252 offset:13312
	ds_read_b64_tr_b16 v[154:155], v252 offset:15360
	v_fmamk_f32 v70, v185, 0x42280000, v187
	v_fmamk_f32 v71, v185, 0x422c0000, v187
	v_fmamk_f32 v72, v185, 0x42400000, v187
	v_fmamk_f32 v73, v185, 0x42440000, v187
	v_fmamk_f32 v74, v185, 0x42480000, v187
	s_waitcnt lgkmcnt(6)
	v_mfma_f32_32x32x16_bf16 v[0:15], v[136:139], v[156:159], v[0:15]
	ds_read_b64_tr_b16 v[156:157], v252 offset:13824
	ds_read_b64_tr_b16 v[158:159], v252 offset:15872
	v_fmamk_f32 v75, v185, 0x424c0000, v187
	v_fmamk_f32 v76, v185, 0x42600000, v187
	v_fmamk_f32 v77, v185, 0x42640000, v187
	v_fmamk_f32 v78, v185, 0x42680000, v187
	v_fmamk_f32 v79, v185, 0x426c0000, v187
	s_waitcnt lgkmcnt(6)
	v_mfma_f32_32x32x16_bf16 v[48:63], v[140:143], v[144:147], v[48:63]
	ds_read_b64_tr_b16 v[144:145], v252 offset:16384
	ds_read_b64_tr_b16 v[146:147], v252 offset:18432
	v_exp_f32_e32 v112, v112
	v_exp_f32_e32 v113, v113
	v_exp_f32_e32 v114, v114
	v_exp_f32_e32 v115, v115
	v_add_f32_e32 v182, v112, v182
	s_waitcnt lgkmcnt(6)
	v_mfma_f32_32x32x16_bf16 v[32:47], v[140:143], v[148:151], v[32:47]
	ds_read_b64_tr_b16 v[148:149], v252 offset:16896
	ds_read_b64_tr_b16 v[150:151], v252 offset:18944
	v_add_f32_e32 v182, v113, v182
	v_cvt_pk_bf16_f32 v128, v112, v113
	v_exp_f32_e32 v116, v116
	v_exp_f32_e32 v117, v117
	v_add_f32_e32 v182, v114, v182
	s_waitcnt lgkmcnt(6)
	v_mfma_f32_32x32x16_bf16 v[16:31], v[140:143], v[152:155], v[16:31]
	ds_read_b64_tr_b16 v[152:153], v252 offset:17408
	ds_read_b64_tr_b16 v[154:155], v252 offset:19456
	v_add_f32_e32 v182, v115, v182
	v_cvt_pk_bf16_f32 v129, v114, v115
	v_exp_f32_e32 v118, v118
	v_exp_f32_e32 v119, v119
	v_add_f32_e32 v182, v116, v182
	s_waitcnt lgkmcnt(6)
	v_mfma_f32_32x32x16_bf16 v[0:15], v[140:143], v[156:159], v[0:15]
	ds_read_b64_tr_b16 v[156:157], v252 offset:17920
	ds_read_b64_tr_b16 v[158:159], v252 offset:19968
	v_add_f32_e32 v182, v117, v182
	v_cvt_pk_bf16_f32 v130, v116, v117
	v_cvt_pk_bf16_f32 v131, v118, v119
	v_add_f32_e32 v182, v118, v182
	v_add_f32_e32 v182, v119, v182
	s_add_i32 s100, s55, 62
	s_cmp_lt_u32 s100, 93
	s_cbranch_scc0 .Lsym_nodiag_s0
	v_add_f32_e32 v190, 0x00000000, v183
	v_add_f32_e32 v191, 0xc2000000, v183
	v_fma_f32 v80, |v190|, v186, s16
	v_fma_f32 v64, |v191|, v186, s16
	v_add_f32_e32 v190, 0xbf800000, v183
	v_add_f32_e32 v191, 0xc2040000, v183
	v_fma_f32 v81, |v190|, v186, s16
	v_fma_f32 v65, |v191|, v186, s16
	v_add_f32_e32 v190, 0xc0000000, v183
	v_add_f32_e32 v191, 0xc2080000, v183
	v_fma_f32 v82, |v190|, v186, s16
	v_fma_f32 v66, |v191|, v186, s16
	v_add_f32_e32 v190, 0xc0400000, v183
	v_add_f32_e32 v191, 0xc20c0000, v183
	v_fma_f32 v83, |v190|, v186, s16
	v_fma_f32 v67, |v191|, v186, s16
	v_add_f32_e32 v190, 0xc1000000, v183
	v_add_f32_e32 v191, 0xc2200000, v183
	v_fma_f32 v84, |v190|, v186, s16
	v_fma_f32 v68, |v191|, v186, s16
	v_add_f32_e32 v190, 0xc1100000, v183
	v_add_f32_e32 v191, 0xc2240000, v183
	v_fma_f32 v85, |v190|, v186, s16
	v_fma_f32 v69, |v191|, v186, s16
	v_add_f32_e32 v190, 0xc1200000, v183
	v_add_f32_e32 v191, 0xc2280000, v183
	v_fma_f32 v86, |v190|, v186, s16
	v_fma_f32 v70, |v191|, v186, s16
	v_add_f32_e32 v190, 0xc1300000, v183
	v_add_f32_e32 v191, 0xc22c0000, v183
	v_fma_f32 v87, |v190|, v186, s16
	v_fma_f32 v71, |v191|, v186, s16
	v_add_f32_e32 v190, 0xc1800000, v183
	v_add_f32_e32 v191, 0xc2400000, v183
	v_fma_f32 v88, |v190|, v186, s16
	v_fma_f32 v72, |v191|, v186, s16
	v_add_f32_e32 v190, 0xc1880000, v183
	v_add_f32_e32 v191, 0xc2440000, v183
	v_fma_f32 v89, |v190|, v186, s16
	v_fma_f32 v73, |v191|, v186, s16
	v_add_f32_e32 v190, 0xc1900000, v183
	v_add_f32_e32 v191, 0xc2480000, v183
	v_fma_f32 v90, |v190|, v186, s16
	v_fma_f32 v74, |v191|, v186, s16
	v_add_f32_e32 v190, 0xc1980000, v183
	v_add_f32_e32 v191, 0xc24c0000, v183
	v_fma_f32 v91, |v190|, v186, s16
	v_fma_f32 v75, |v191|, v186, s16
	v_add_f32_e32 v190, 0xc1c00000, v183
	v_add_f32_e32 v191, 0xc2600000, v183
	v_fma_f32 v92, |v190|, v186, s16
	v_fma_f32 v76, |v191|, v186, s16
	v_add_f32_e32 v190, 0xc1c80000, v183
	v_add_f32_e32 v191, 0xc2640000, v183
	v_fma_f32 v93, |v190|, v186, s16
	v_fma_f32 v77, |v191|, v186, s16
	v_add_f32_e32 v190, 0xc1d00000, v183
	v_add_f32_e32 v191, 0xc2680000, v183
	v_fma_f32 v94, |v190|, v186, s16
	v_fma_f32 v78, |v191|, v186, s16
	v_add_f32_e32 v190, 0xc1d80000, v183
	v_add_f32_e32 v191, 0xc26c0000, v183
	v_fma_f32 v95, |v190|, v186, s16
	v_fma_f32 v79, |v191|, v186, s16

; #define SBAR() __builtin_amdgcn_sched_barrier(0)
; #define PK4(P, BASE, OUT) do { u32x4 w = {cvtpk(P[BASE + 0], P[BASE + 1]), cvtpk(P[BASE + 2], P[BASE + 3]), cvtpk(P[BASE + 4], P[BASE + 5]), cvtpk(P[BASE + 6], P[BASE + 7])}; \
;     OUT = *reinterpret_cast<bf16x8*>(&w); } while (0)
; template <int KS> __device__ __forceinline__ void pv_ks(f32x16* o, int vb, bf16x8 pa) {
;     const s16x4 l0 = tr_read<v_rd_off(0, KS, 0)>(vb), h0 = tr_read<v_rd_off(0, KS, 1)>(vb), l1 = tr_read<v_rd_off(1, KS, 0)>(vb), h1 = tr_read<v_rd_off(1, KS, 1)>(vb);
;     const s16x4 l2 = tr_read<v_rd_off(2, KS, 0)>(vb), h2 = tr_read<v_rd_off(2, KS, 1)>(vb), l3 = tr_read<v_rd_off(3, KS, 0)>(vb), h3 = tr_read<v_rd_off(3, KS, 1)>(vb);
;     ...
;     asm volatile("s_waitcnt lgkmcnt(6)" ::: "memory"); SBAR();
;     o[0] = __builtin_amdgcn_mfma_f32_32x32x16_bf16(pa, PK(l0, h0), o[0], 0, 0, 0);
;     asm volatile("s_waitcnt lgkmcnt(4)" ::: "memory"); SBAR();
;     o[1] = __builtin_amdgcn_mfma_f32_32x32x16_bf16(pa, PK(l1, h1), o[1], 0, 0, 0);
;     asm volatile("s_waitcnt lgkmcnt(2)" ::: "memory"); SBAR();
;     o[2] = __builtin_amdgcn_mfma_f32_32x32x16_bf16(pa, PK(l2, h2), o[2], 0, 0, 0);
;     asm volatile("s_waitcnt lgkmcnt(0)" ::: "memory"); SBAR();
;     o[3] = __builtin_amdgcn_mfma_f32_32x32x16_bf16(pa, PK(l3, h3), o[3], 0, 0, 0);
;     ...
; }
; __device__ __forceinline__ void pv_d0(f32x16* o, int vb, bf16x8 pa0, bf16x8 pa1, bf16x8 pa2, bf16x8 pa3) {
;     __builtin_amdgcn_s_setprio(1);
;     pv_ks<0>(o, vb, pa0); pv_ks<1>(o, vb, pa1); pv_ks<2>(o, vb, pa2); pv_ks<3>(o, vb, pa3);
;     __builtin_amdgcn_s_setprio(0);
; }
; __device__ __forceinline__ void exp_half(f32x16& p) {
; #pragma unroll
;     for (int r = 0; r < 16; ++r) p[r] = __builtin_amdgcn_exp2f(p[r]);
; }
; __device__ __forceinline__ void pack_p(const f32x16& p0, const f32x16& p1, float& l_reg, bf16x8& pa0, bf16x8& pa1, bf16x8& pa2, bf16x8& pa3) {
;     float ps = 0;
; #pragma unroll
;     for (int r = 0; r < 16; ++r) ps += p0[r];
; #pragma unroll
;     for (int r = 0; r < 16; ++r) ps += p1[r];
;     l_reg += ps;
;     ...
;     PK4(p0, 0, pa0); PK4(p0, 8, pa1); PK4(p1, 0, pa2); PK4(p1, 8, pa3);
;     ...
; }
.Lsym_nostage_s1:
	s_waitcnt lgkmcnt(14)
	v_mfma_f32_32x32x16_bf16 v[48:63], v[128:131], v[144:147], v[48:63]
	ds_read_b64_tr_b16 v[144:145], v252 offset:20480
	ds_read_b64_tr_b16 v[146:147], v252 offset:22528
	v_exp_f32_e32 v120, v120
	v_exp_f32_e32 v121, v121
	v_exp_f32_e32 v122, v122
	v_exp_f32_e32 v123, v123
	v_add_f32_e32 v182, v120, v182
	s_waitcnt lgkmcnt(9)
	v_mfma_f32_32x32x16_bf16 v[80:95], v[192:195], v[172:175], v[80:95]
	v_add_f32_e32 v182, v121, v182
	v_cvt_pk_bf16_f32 v132, v120, v121
	v_exp_f32_e32 v124, v124
	v_exp_f32_e32 v125, v125
	v_mfma_f32_32x32x16_bf16 v[32:47], v[128:131], v[148:151], v[32:47]
	ds_read_b64_tr_b16 v[148:149], v252 offset:20992
	ds_read_b64_tr_b16 v[150:151], v252 offset:23040
	v_add_f32_e32 v182, v122, v182
	v_add_f32_e32 v182, v123, v182
	v_cvt_pk_bf16_f32 v133, v122, v123
	v_exp_f32_e32 v126, v126
	v_exp_f32_e32 v127, v127
	s_waitcnt lgkmcnt(10)
	v_mfma_f32_32x32x16_bf16 v[64:79], v[196:199], v[172:175], v[64:79]
	v_add_f32_e32 v182, v124, v182
	v_add_f32_e32 v182, v125, v182
	v_cvt_pk_bf16_f32 v134, v124, v125
	v_cvt_pk_bf16_f32 v135, v126, v127
	v_mfma_f32_32x32x16_bf16 v[16:31], v[128:131], v[152:155], v[16:31]
	ds_read_b64_tr_b16 v[152:153], v252 offset:21504
	ds_read_b64_tr_b16 v[154:155], v252 offset:23552
	v_add_f32_e32 v182, v126, v182
	v_add_f32_e32 v182, v127, v182
	v_exp_f32_e32 v96, v96
	v_exp_f32_e32 v97, v97
	v_exp_f32_e32 v98, v98
	s_waitcnt lgkmcnt(11)
	v_mfma_f32_32x32x16_bf16 v[80:95], v[200:203], v[168:171], v[80:95]
	v_exp_f32_e32 v99, v99
	v_add_f32_e32 v182, v96, v182
	v_add_f32_e32 v182, v97, v182
	v_cvt_pk_bf16_f32 v136, v96, v97
	v_mfma_f32_32x32x16_bf16 v[0:15], v[128:131], v[156:159], v[0:15]
	ds_read_b64_tr_b16 v[156:157], v252 offset:22016
	ds_read_b64_tr_b16 v[158:159], v252 offset:24064
	v_exp_f32_e32 v100, v100
	v_exp_f32_e32 v101, v101
	v_add_f32_e32 v182, v98, v182
	v_add_f32_e32 v182, v99, v182
	v_cvt_pk_bf16_f32 v137, v98, v99
	s_waitcnt lgkmcnt(12)
	v_mfma_f32_32x32x16_bf16 v[64:79], v[204:207], v[168:171], v[64:79]
	v_exp_f32_e32 v102, v102
	v_exp_f32_e32 v103, v103
	v_add_f32_e32 v182, v100, v182
	v_add_f32_e32 v182, v101, v182
	s_waitcnt lgkmcnt(6)
	v_mfma_f32_32x32x16_bf16 v[48:63], v[132:135], v[144:147], v[48:63]
	ds_read_b64_tr_b16 v[144:145], v252 offset:24576
	ds_read_b64_tr_b16 v[146:147], v252 offset:26624
	v_cvt_pk_bf16_f32 v138, v100, v101
	v_cvt_pk_bf16_f32 v139, v102, v103
	v_add_f32_e32 v182, v102, v182
	v_add_f32_e32 v182, v103, v182
	v_exp_f32_e32 v104, v104
	v_mfma_f32_32x32x16_bf16 v[80:95], v[208:211], v[164:167], v[80:95]
	v_exp_f32_e32 v105, v105
	v_exp_f32_e32 v106, v106
	v_exp_f32_e32 v107, v107
	v_add_f32_e32 v182, v104, v182
	v_add_f32_e32 v182, v105, v182
	s_waitcnt lgkmcnt(6)
	v_mfma_f32_32x32x16_bf16 v[32:47], v[132:135], v[148:151], v[32:47]
	ds_read_b64_tr_b16 v[148:149], v252 offset:25088
	ds_read_b64_tr_b16 v[150:151], v252 offset:27136
	v_cvt_pk_bf16_f32 v140, v104, v105
	v_exp_f32_e32 v108, v108
	v_exp_f32_e32 v109, v109
	v_add_f32_e32 v182, v106, v182
	v_add_f32_e32 v182, v107, v182
	v_mfma_f32_32x32x16_bf16 v[64:79], v[212:215], v[164:167], v[64:79]
	v_cvt_pk_bf16_f32 v141, v106, v107
	v_exp_f32_e32 v110, v110
	v_exp_f32_e32 v111, v111
	v_add_f32_e32 v182, v108, v182
	v_add_f32_e32 v182, v109, v182
	s_waitcnt lgkmcnt(6)
	v_mfma_f32_32x32x16_bf16 v[16:31], v[132:135], v[152:155], v[16:31]
	ds_read_b64_tr_b16 v[152:153], v252 offset:25600
	ds_read_b64_tr_b16 v[154:155], v252 offset:27648
	v_cvt_pk_bf16_f32 v142, v108, v109
	v_cvt_pk_bf16_f32 v143, v110, v111
	v_add_f32_e32 v182, v110, v182
	v_add_f32_e32 v182, v111, v182
	s_cmp_lt_i32 s55, 0
	v_mfma_f32_32x32x16_bf16 v[80:95], v[216:219], v[160:163], v[80:95]
	s_cselect_b32 s100, -1.0, 1.0
	v_mul_f32_e32 v185, s100, v186
	v_fma_f32 v187, -v185, v183, s16
	v_fmamk_f32 v112, v185, 0x00000000, v187
	v_fmamk_f32 v113, v185, 0x3f800000, v187
	s_waitcnt lgkmcnt(6)
	v_mfma_f32_32x32x16_bf16 v[0:15], v[132:135], v[156:159], v[0:15]
	ds_read_b64_tr_b16 v[156:157], v252 offset:26112
	ds_read_b64_tr_b16 v[158:159], v252 offset:28160
	v_fmamk_f32 v114, v185, 0x40000000, v187
	v_fmamk_f32 v115, v185, 0x40400000, v187
	v_fmamk_f32 v116, v185, 0x41000000, v187
	v_fmamk_f32 v117, v185, 0x41100000, v187
	v_fmamk_f32 v118, v185, 0x41200000, v187
	v_mfma_f32_32x32x16_bf16 v[64:79], v[220:223], v[160:163], v[64:79]
	v_fmamk_f32 v119, v185, 0x41300000, v187
	v_fmamk_f32 v120, v185, 0x41800000, v187
	v_fmamk_f32 v121, v185, 0x41880000, v187
	v_fmamk_f32 v122, v185, 0x41900000, v187
	v_fmamk_f32 v123, v185, 0x41980000, v187
	s_waitcnt lgkmcnt(6)
	v_mfma_f32_32x32x16_bf16 v[48:63], v[136:139], v[144:147], v[48:63]
	ds_read_b64_tr_b16 v[144:145], v252 offset:28672
	ds_read_b64_tr_b16 v[146:147], v252 offset:30720
	v_fmamk_f32 v124, v185, 0x41c00000, v187
	v_fmamk_f32 v125, v185, 0x41c80000, v187
	v_fmamk_f32 v126, v185, 0x41d00000, v187
	v_fmamk_f32 v127, v185, 0x41d80000, v187
	v_fmamk_f32 v96, v185, 0x42000000, v187
	s_waitcnt lgkmcnt(6)
; #define SBAR() __builtin_amdgcn_sched_barrier(0)
; template <int KS> __device__ __forceinline__ void pv_ks(f32x16* o, int vb, bf16x8 pa) {
;     const s16x4 l0 = tr_read<v_rd_off(0, KS, 0)>(vb), h0 = tr_read<v_rd_off(0, KS, 1)>(vb), l1 = tr_read<v_rd_off(1, KS, 0)>(vb), h1 = tr_read<v_rd_off(1, KS, 1)>(vb);
;     const s16x4 l2 = tr_read<v_rd_off(2, KS, 0)>(vb), h2 = tr_read<v_rd_off(2, KS, 1)>(vb), l3 = tr_read<v_rd_off(3, KS, 0)>(vb), h3 = tr_read<v_rd_off(3, KS, 1)>(vb);
;     ...
;     asm volatile("s_waitcnt lgkmcnt(6)" ::: "memory"); SBAR();
;     o[0] = __builtin_amdgcn_mfma_f32_32x32x16_bf16(pa, PK(l0, h0), o[0], 0, 0, 0);
;     asm volatile("s_waitcnt lgkmcnt(4)" ::: "memory"); SBAR();
;     o[1] = __builtin_amdgcn_mfma_f32_32x32x16_bf16(pa, PK(l1, h1), o[1], 0, 0, 0);
;     asm volatile("s_waitcnt lgkmcnt(2)" ::: "memory"); SBAR();
;     o[2] = __builtin_amdgcn_mfma_f32_32x32x16_bf16(pa, PK(l2, h2), o[2], 0, 0, 0);
;     asm volatile("s_waitcnt lgkmcnt(0)" ::: "memory"); SBAR();
;     o[3] = __builtin_amdgcn_mfma_f32_32x32x16_bf16(pa, PK(l3, h3), o[3], 0, 0, 0);
;     ...
; }
; __device__ __forceinline__ void pv_d0(f32x16* o, int vb, bf16x8 pa0, bf16x8 pa1, bf16x8 pa2, bf16x8 pa3) {
;     __builtin_amdgcn_s_setprio(1);
;     pv_ks<0>(o, vb, pa0); pv_ks<1>(o, vb, pa1); pv_ks<2>(o, vb, pa2); pv_ks<3>(o, vb, pa3);
;     __builtin_amdgcn_s_setprio(0);
; }
; __device__ __forceinline__ void exp_half(f32x16& p) {
; #pragma unroll
;     for (int r = 0; r < 16; ++r) p[r] = __builtin_amdgcn_exp2f(p[r]);
; }
; __device__ __forceinline__ void pack_p(const f32x16& p0, const f32x16& p1, float& l_reg, bf16x8& pa0, bf16x8& pa1, bf16x8& pa2, bf16x8& pa3) {
;     float ps = 0;
; #pragma unroll
;     for (int r = 0; r < 16; ++r) ps += p0[r];
; #pragma unroll
;     for (int r = 0; r < 16; ++r) ps += p1[r];
;     l_reg += ps;
;     ...
;     PK4(p0, 0, pa0); PK4(p0, 8, pa1); PK4(p1, 0, pa2); PK4(p1, 8, pa3);
;     ...
; }
; __device__ __forceinline__ void bias_init(f32x16& p0, f32x16& p1, float base, float nslope2, float nM2, int rel  ) {
;     if (rel <= -63 || rel >= 31) {
;         const float sg = (rel < 0) ? -nslope2 : nslope2, lbv = fmaf(-sg, base, nM2);
; #pragma unroll
;         for (int r = 0; r < 16; ++r) { p0[r] = fmaf((float)((r & 3) + 8 * (r >> 2)), sg, lbv); p1[r] = fmaf((float)((r & 3) + 8 * (r >> 2) + 32), sg, lbv); }
;     } else {
; #pragma unroll
	v_mfma_f32_32x32x16_bf16 v[32:47], v[136:139], v[148:151], v[32:47]
	ds_read_b64_tr_b16 v[148:149], v252 offset:29184
	ds_read_b64_tr_b16 v[150:151], v252 offset:31232
	v_fmamk_f32 v97, v185, 0x42040000, v187
	v_fmamk_f32 v98, v185, 0x42080000, v187
	v_fmamk_f32 v99, v185, 0x420c0000, v187
	v_fmamk_f32 v100, v185, 0x42200000, v187
	v_fmamk_f32 v101, v185, 0x42240000, v187
	s_waitcnt lgkmcnt(6)
	v_mfma_f32_32x32x16_bf16 v[16:31], v[136:139], v[152:155], v[16:31]
	ds_read_b64_tr_b16 v[152:153], v252 offset:29696
	ds_read_b64_tr_b16 v[154:155], v252 offset:31744
	v_fmamk_f32 v102, v185, 0x42280000, v187
	v_fmamk_f32 v103, v185, 0x422c0000, v187
	v_fmamk_f32 v104, v185, 0x42400000, v187
	v_fmamk_f32 v105, v185, 0x42440000, v187
	v_fmamk_f32 v106, v185, 0x42480000, v187
	s_waitcnt lgkmcnt(6)
	v_mfma_f32_32x32x16_bf16 v[0:15], v[136:139], v[156:159], v[0:15]
	ds_read_b64_tr_b16 v[156:157], v252 offset:30208
	ds_read_b64_tr_b16 v[158:159], v252 offset:32256
	v_fmamk_f32 v107, v185, 0x424c0000, v187
	v_fmamk_f32 v108, v185, 0x42600000, v187
	v_fmamk_f32 v109, v185, 0x42640000, v187
	v_fmamk_f32 v110, v185, 0x42680000, v187
	v_fmamk_f32 v111, v185, 0x426c0000, v187
	s_waitcnt lgkmcnt(6)
	v_mfma_f32_32x32x16_bf16 v[48:63], v[140:143], v[144:147], v[48:63]
	ds_read_b64_tr_b16 v[144:145], v252 offset:32768
	ds_read_b64_tr_b16 v[146:147], v252 offset:34816
	v_exp_f32_e32 v80, v80
	v_exp_f32_e32 v81, v81
	v_exp_f32_e32 v82, v82
	v_exp_f32_e32 v83, v83
	v_add_f32_e32 v182, v80, v182
	s_waitcnt lgkmcnt(6)
	v_mfma_f32_32x32x16_bf16 v[32:47], v[140:143], v[148:151], v[32:47]
	ds_read_b64_tr_b16 v[148:149], v252 offset:33280
	ds_read_b64_tr_b16 v[150:151], v252 offset:35328
	v_add_f32_e32 v182, v81, v182
	v_cvt_pk_bf16_f32 v128, v80, v81
	v_exp_f32_e32 v84, v84
	v_exp_f32_e32 v85, v85
	v_add_f32_e32 v182, v82, v182
	s_waitcnt lgkmcnt(6)
	v_mfma_f32_32x32x16_bf16 v[16:31], v[140:143], v[152:155], v[16:31]
	ds_read_b64_tr_b16 v[152:153], v252 offset:33792
	ds_read_b64_tr_b16 v[154:155], v252 offset:35840
	v_add_f32_e32 v182, v83, v182
	v_cvt_pk_bf16_f32 v129, v82, v83
	v_exp_f32_e32 v86, v86
	v_exp_f32_e32 v87, v87
	v_add_f32_e32 v182, v84, v182
	s_waitcnt lgkmcnt(6)
	v_mfma_f32_32x32x16_bf16 v[0:15], v[140:143], v[156:159], v[0:15]
	ds_read_b64_tr_b16 v[156:157], v252 offset:34304
	ds_read_b64_tr_b16 v[158:159], v252 offset:36352
	v_add_f32_e32 v182, v85, v182
	v_cvt_pk_bf16_f32 v130, v84, v85
	v_cvt_pk_bf16_f32 v131, v86, v87
	v_add_f32_e32 v182, v86, v182
	v_add_f32_e32 v182, v87, v182
	s_add_i32 s100, s55, 62
	s_cmp_lt_u32 s100, 93
	s_cbranch_scc0 .Lsym_nodiag_s1
	v_add_f32_e32 v190, 0x00000000, v183
	v_add_f32_e32 v191, 0xc2000000, v183
	v_fma_f32 v112, |v190|, v186, s16
	v_fma_f32 v96, |v191|, v186, s16
	v_add_f32_e32 v190, 0xbf800000, v183
	v_add_f32_e32 v191, 0xc2040000, v183
	v_fma_f32 v113, |v190|, v186, s16
	v_fma_f32 v97, |v191|, v186, s16
	v_add_f32_e32 v190, 0xc0000000, v183
	v_add_f32_e32 v191, 0xc2080000, v183
	v_fma_f32 v114, |v190|, v186, s16
	v_fma_f32 v98, |v191|, v186, s16
	v_add_f32_e32 v190, 0xc0400000, v183
	v_add_f32_e32 v191, 0xc20c0000, v183
	v_fma_f32 v115, |v190|, v186, s16
	v_fma_f32 v99, |v191|, v186, s16
	v_add_f32_e32 v190, 0xc1000000, v183
	v_add_f32_e32 v191, 0xc2200000, v183
	v_fma_f32 v116, |v190|, v186, s16
	v_fma_f32 v100, |v191|, v186, s16
	v_add_f32_e32 v190, 0xc1100000, v183
	v_add_f32_e32 v191, 0xc2240000, v183
	v_fma_f32 v117, |v190|, v186, s16
	v_fma_f32 v101, |v191|, v186, s16
	v_add_f32_e32 v190, 0xc1200000, v183
	v_add_f32_e32 v191, 0xc2280000, v183
	v_fma_f32 v118, |v190|, v186, s16
	v_fma_f32 v102, |v191|, v186, s16
	v_add_f32_e32 v190, 0xc1300000, v183
	v_add_f32_e32 v191, 0xc22c0000, v183
	v_fma_f32 v119, |v190|, v186, s16
	v_fma_f32 v103, |v191|, v186, s16
	v_add_f32_e32 v190, 0xc1800000, v183
	v_add_f32_e32 v191, 0xc2400000, v183
	v_fma_f32 v120, |v190|, v186, s16
	v_fma_f32 v104, |v191|, v186, s16
	v_add_f32_e32 v190, 0xc1880000, v183
	v_add_f32_e32 v191, 0xc2440000, v183
	v_fma_f32 v121, |v190|, v186, s16
	v_fma_f32 v105, |v191|, v186, s16
	v_add_f32_e32 v190, 0xc1900000, v183
	v_add_f32_e32 v191, 0xc2480000, v183
	v_fma_f32 v122, |v190|, v186, s16
	v_fma_f32 v106, |v191|, v186, s16
	v_add_f32_e32 v190, 0xc1980000, v183
	v_add_f32_e32 v191, 0xc24c0000, v183
	v_fma_f32 v123, |v190|, v186, s16
	v_fma_f32 v107, |v191|, v186, s16
	v_add_f32_e32 v190, 0xc1c00000, v183
	v_add_f32_e32 v191, 0xc2600000, v183
	v_fma_f32 v124, |v190|, v186, s16
	v_fma_f32 v108, |v191|, v186, s16
	v_add_f32_e32 v190, 0xc1c80000, v183
	v_add_f32_e32 v191, 0xc2640000, v183
	v_fma_f32 v125, |v190|, v186, s16
	v_fma_f32 v109, |v191|, v186, s16
	v_add_f32_e32 v190, 0xc1d00000, v183
	v_add_f32_e32 v191, 0xc2680000, v183
	v_fma_f32 v126, |v190|, v186, s16
	v_fma_f32 v110, |v191|, v186, s16
	v_add_f32_e32 v190, 0xc1d80000, v183
	v_add_f32_e32 v191, 0xc26c0000, v183
	v_fma_f32 v127, |v190|, v186, s16
	v_fma_f32 v111, |v191|, v186, s16

; #define SBAR() __builtin_amdgcn_sched_barrier(0)
; #define PK4(P, BASE, OUT) do { u32x4 w = {cvtpk(P[BASE + 0], P[BASE + 1]), cvtpk(P[BASE + 2], P[BASE + 3]), cvtpk(P[BASE + 4], P[BASE + 5]), cvtpk(P[BASE + 6], P[BASE + 7])}; \
;     OUT = *reinterpret_cast<bf16x8*>(&w); } while (0)
; template <int KS> __device__ __forceinline__ void pv_ks(f32x16* o, int vb, bf16x8 pa) {
;     const s16x4 l0 = tr_read<v_rd_off(0, KS, 0)>(vb), h0 = tr_read<v_rd_off(0, KS, 1)>(vb), l1 = tr_read<v_rd_off(1, KS, 0)>(vb), h1 = tr_read<v_rd_off(1, KS, 1)>(vb);
;     const s16x4 l2 = tr_read<v_rd_off(2, KS, 0)>(vb), h2 = tr_read<v_rd_off(2, KS, 1)>(vb), l3 = tr_read<v_rd_off(3, KS, 0)>(vb), h3 = tr_read<v_rd_off(3, KS, 1)>(vb);
;     ...
;     asm volatile("s_waitcnt lgkmcnt(6)" ::: "memory"); SBAR();
;     o[0] = __builtin_amdgcn_mfma_f32_32x32x16_bf16(pa, PK(l0, h0), o[0], 0, 0, 0);
;     asm volatile("s_waitcnt lgkmcnt(4)" ::: "memory"); SBAR();
;     o[1] = __builtin_amdgcn_mfma_f32_32x32x16_bf16(pa, PK(l1, h1), o[1], 0, 0, 0);
;     asm volatile("s_waitcnt lgkmcnt(2)" ::: "memory"); SBAR();
;     o[2] = __builtin_amdgcn_mfma_f32_32x32x16_bf16(pa, PK(l2, h2), o[2], 0, 0, 0);
;     asm volatile("s_waitcnt lgkmcnt(0)" ::: "memory"); SBAR();
;     o[3] = __builtin_amdgcn_mfma_f32_32x32x16_bf16(pa, PK(l3, h3), o[3], 0, 0, 0);
;     ...
; }
; __device__ __forceinline__ void pv_d0(f32x16* o, int vb, bf16x8 pa0, bf16x8 pa1, bf16x8 pa2, bf16x8 pa3) {
;     __builtin_amdgcn_s_setprio(1);
;     pv_ks<0>(o, vb, pa0); pv_ks<1>(o, vb, pa1); pv_ks<2>(o, vb, pa2); pv_ks<3>(o, vb, pa3);
;     __builtin_amdgcn_s_setprio(0);
; }
; __device__ __forceinline__ void exp_half(f32x16& p) {
; #pragma unroll
;     for (int r = 0; r < 16; ++r) p[r] = __builtin_amdgcn_exp2f(p[r]);
; }
; __device__ __forceinline__ void pack_p(const f32x16& p0, const f32x16& p1, float& l_reg, bf16x8& pa0, bf16x8& pa1, bf16x8& pa2, bf16x8& pa3) {
;     float ps = 0;
; #pragma unroll
;     for (int r = 0; r < 16; ++r) ps += p0[r];
; #pragma unroll
;     for (int r = 0; r < 16; ++r) ps += p1[r];
;     l_reg += ps;
;     ...
;     PK4(p0, 0, pa0); PK4(p0, 8, pa1); PK4(p1, 0, pa2); PK4(p1, 8, pa3);
;     ...
; }
.Lsym_nostage_s2:
	s_waitcnt lgkmcnt(14)
	v_mfma_f32_32x32x16_bf16 v[48:63], v[128:131], v[144:147], v[48:63]
	ds_read_b64_tr_b16 v[144:145], v252 offset:36864
	ds_read_b64_tr_b16 v[146:147], v252 offset:38912
	v_exp_f32_e32 v88, v88
	v_exp_f32_e32 v89, v89
	v_exp_f32_e32 v90, v90
	v_exp_f32_e32 v91, v91
	v_add_f32_e32 v182, v88, v182
	s_waitcnt lgkmcnt(9)
	v_mfma_f32_32x32x16_bf16 v[112:127], v[192:195], v[172:175], v[112:127]
	v_add_f32_e32 v182, v89, v182
	v_cvt_pk_bf16_f32 v132, v88, v89
	v_exp_f32_e32 v92, v92
	v_exp_f32_e32 v93, v93
	v_mfma_f32_32x32x16_bf16 v[32:47], v[128:131], v[148:151], v[32:47]
	ds_read_b64_tr_b16 v[148:149], v252 offset:37376
	ds_read_b64_tr_b16 v[150:151], v252 offset:39424
	v_add_f32_e32 v182, v90, v182
	v_add_f32_e32 v182, v91, v182
	v_cvt_pk_bf16_f32 v133, v90, v91
	v_exp_f32_e32 v94, v94
	v_exp_f32_e32 v95, v95
	s_waitcnt lgkmcnt(10)
	v_mfma_f32_32x32x16_bf16 v[96:111], v[196:199], v[172:175], v[96:111]
	v_add_f32_e32 v182, v92, v182
	v_add_f32_e32 v182, v93, v182
	v_cvt_pk_bf16_f32 v134, v92, v93
	v_cvt_pk_bf16_f32 v135, v94, v95
	v_mfma_f32_32x32x16_bf16 v[16:31], v[128:131], v[152:155], v[16:31]
	ds_read_b64_tr_b16 v[152:153], v252 offset:37888
	ds_read_b64_tr_b16 v[154:155], v252 offset:39936
	v_add_f32_e32 v182, v94, v182
	v_add_f32_e32 v182, v95, v182
	v_exp_f32_e32 v64, v64
	v_exp_f32_e32 v65, v65
	v_exp_f32_e32 v66, v66
	s_waitcnt lgkmcnt(11)
	v_mfma_f32_32x32x16_bf16 v[112:127], v[200:203], v[168:171], v[112:127]
	v_exp_f32_e32 v67, v67
	v_add_f32_e32 v182, v64, v182
	v_add_f32_e32 v182, v65, v182
	v_cvt_pk_bf16_f32 v136, v64, v65
	v_mfma_f32_32x32x16_bf16 v[0:15], v[128:131], v[156:159], v[0:15]
	ds_read_b64_tr_b16 v[156:157], v252 offset:38400
	ds_read_b64_tr_b16 v[158:159], v252 offset:40448
	v_exp_f32_e32 v68, v68
	v_exp_f32_e32 v69, v69
	v_add_f32_e32 v182, v66, v182
	v_add_f32_e32 v182, v67, v182
	v_cvt_pk_bf16_f32 v137, v66, v67
	s_waitcnt lgkmcnt(12)
	v_mfma_f32_32x32x16_bf16 v[96:111], v[204:207], v[168:171], v[96:111]
	v_exp_f32_e32 v70, v70
	v_exp_f32_e32 v71, v71
	v_add_f32_e32 v182, v68, v182
	v_add_f32_e32 v182, v69, v182
	s_waitcnt lgkmcnt(6)
	v_mfma_f32_32x32x16_bf16 v[48:63], v[132:135], v[144:147], v[48:63]
	ds_read_b64_tr_b16 v[144:145], v252 offset:40960
	ds_read_b64_tr_b16 v[146:147], v252 offset:43008
	v_cvt_pk_bf16_f32 v138, v68, v69
	v_cvt_pk_bf16_f32 v139, v70, v71
	v_add_f32_e32 v182, v70, v182
	v_add_f32_e32 v182, v71, v182
	v_exp_f32_e32 v72, v72
	v_mfma_f32_32x32x16_bf16 v[112:127], v[208:211], v[164:167], v[112:127]
	v_exp_f32_e32 v73, v73
	v_exp_f32_e32 v74, v74
	v_exp_f32_e32 v75, v75
	v_add_f32_e32 v182, v72, v182
	v_add_f32_e32 v182, v73, v182
	s_waitcnt lgkmcnt(6)
	v_mfma_f32_32x32x16_bf16 v[32:47], v[132:135], v[148:151], v[32:47]
	ds_read_b64_tr_b16 v[148:149], v252 offset:41472
	ds_read_b64_tr_b16 v[150:151], v252 offset:43520
	v_cvt_pk_bf16_f32 v140, v72, v73
	v_exp_f32_e32 v76, v76
	v_exp_f32_e32 v77, v77
	v_add_f32_e32 v182, v74, v182
	v_add_f32_e32 v182, v75, v182
	v_mfma_f32_32x32x16_bf16 v[96:111], v[212:215], v[164:167], v[96:111]
	v_cvt_pk_bf16_f32 v141, v74, v75
	v_exp_f32_e32 v78, v78
	v_exp_f32_e32 v79, v79
	v_add_f32_e32 v182, v76, v182
	v_add_f32_e32 v182, v77, v182
	s_waitcnt lgkmcnt(6)
	v_mfma_f32_32x32x16_bf16 v[16:31], v[132:135], v[152:155], v[16:31]
	ds_read_b64_tr_b16 v[152:153], v252 offset:41984
	ds_read_b64_tr_b16 v[154:155], v252 offset:44032
	v_cvt_pk_bf16_f32 v142, v76, v77
	v_cvt_pk_bf16_f32 v143, v78, v79
	v_add_f32_e32 v182, v78, v182
	v_add_f32_e32 v182, v79, v182
	s_cmp_lt_i32 s55, 0
	v_mfma_f32_32x32x16_bf16 v[112:127], v[216:219], v[160:163], v[112:127]
	s_cselect_b32 s100, -1.0, 1.0
	v_mul_f32_e32 v185, s100, v186
	v_fma_f32 v187, -v185, v183, s16
	v_fmamk_f32 v80, v185, 0x00000000, v187
	v_fmamk_f32 v81, v185, 0x3f800000, v187
	s_waitcnt lgkmcnt(6)
	v_mfma_f32_32x32x16_bf16 v[0:15], v[132:135], v[156:159], v[0:15]
	ds_read_b64_tr_b16 v[156:157], v252 offset:42496
	ds_read_b64_tr_b16 v[158:159], v252 offset:44544
	v_fmamk_f32 v82, v185, 0x40000000, v187
	v_fmamk_f32 v83, v185, 0x40400000, v187
	v_fmamk_f32 v84, v185, 0x41000000, v187
	v_fmamk_f32 v85, v185, 0x41100000, v187
	v_fmamk_f32 v86, v185, 0x41200000, v187
	v_mfma_f32_32x32x16_bf16 v[96:111], v[220:223], v[160:163], v[96:111]
	v_fmamk_f32 v87, v185, 0x41300000, v187
	v_fmamk_f32 v88, v185, 0x41800000, v187
	v_fmamk_f32 v89, v185, 0x41880000, v187
	v_fmamk_f32 v90, v185, 0x41900000, v187
	v_fmamk_f32 v91, v185, 0x41980000, v187
	s_waitcnt lgkmcnt(6)
	v_mfma_f32_32x32x16_bf16 v[48:63], v[136:139], v[144:147], v[48:63]
	ds_read_b64_tr_b16 v[144:145], v252 offset:45056
	ds_read_b64_tr_b16 v[146:147], v252 offset:47104
	v_fmamk_f32 v92, v185, 0x41c00000, v187
	v_fmamk_f32 v93, v185, 0x41c80000, v187
	v_fmamk_f32 v94, v185, 0x41d00000, v187
	v_fmamk_f32 v95, v185, 0x41d80000, v187
	v_fmamk_f32 v64, v185, 0x42000000, v187
	s_waitcnt lgkmcnt(6)
; #define SBAR() __builtin_amdgcn_sched_barrier(0)
; template <int KS> __device__ __forceinline__ void pv_ks(f32x16* o, int vb, bf16x8 pa) {
;     const s16x4 l0 = tr_read<v_rd_off(0, KS, 0)>(vb), h0 = tr_read<v_rd_off(0, KS, 1)>(vb), l1 = tr_read<v_rd_off(1, KS, 0)>(vb), h1 = tr_read<v_rd_off(1, KS, 1)>(vb);
;     const s16x4 l2 = tr_read<v_rd_off(2, KS, 0)>(vb), h2 = tr_read<v_rd_off(2, KS, 1)>(vb), l3 = tr_read<v_rd_off(3, KS, 0)>(vb), h3 = tr_read<v_rd_off(3, KS, 1)>(vb);
;     ...
;     asm volatile("s_waitcnt lgkmcnt(6)" ::: "memory"); SBAR();
;     o[0] = __builtin_amdgcn_mfma_f32_32x32x16_bf16(pa, PK(l0, h0), o[0], 0, 0, 0);
;     asm volatile("s_waitcnt lgkmcnt(4)" ::: "memory"); SBAR();
;     o[1] = __builtin_amdgcn_mfma_f32_32x32x16_bf16(pa, PK(l1, h1), o[1], 0, 0, 0);
;     asm volatile("s_waitcnt lgkmcnt(2)" ::: "memory"); SBAR();
;     o[2] = __builtin_amdgcn_mfma_f32_32x32x16_bf16(pa, PK(l2, h2), o[2], 0, 0, 0);
;     asm volatile("s_waitcnt lgkmcnt(0)" ::: "memory"); SBAR();
;     o[3] = __builtin_amdgcn_mfma_f32_32x32x16_bf16(pa, PK(l3, h3), o[3], 0, 0, 0);
;     ...
; }
; __device__ __forceinline__ void pv_d0(f32x16* o, int vb, bf16x8 pa0, bf16x8 pa1, bf16x8 pa2, bf16x8 pa3) {
;     __builtin_amdgcn_s_setprio(1);
;     pv_ks<0>(o, vb, pa0); pv_ks<1>(o, vb, pa1); pv_ks<2>(o, vb, pa2); pv_ks<3>(o, vb, pa3);
;     __builtin_amdgcn_s_setprio(0);
; }
; __device__ __forceinline__ void exp_half(f32x16& p) {
; #pragma unroll
;     for (int r = 0; r < 16; ++r) p[r] = __builtin_amdgcn_exp2f(p[r]);
; }
; __device__ __forceinline__ void pack_p(const f32x16& p0, const f32x16& p1, float& l_reg, bf16x8& pa0, bf16x8& pa1, bf16x8& pa2, bf16x8& pa3) {
;     float ps = 0;
; #pragma unroll
;     for (int r = 0; r < 16; ++r) ps += p0[r];
; #pragma unroll
;     for (int r = 0; r < 16; ++r) ps += p1[r];
;     l_reg += ps;
;     ...
;     PK4(p0, 0, pa0); PK4(p0, 8, pa1); PK4(p1, 0, pa2); PK4(p1, 8, pa3);
;     ...
; }
; __device__ __forceinline__ void bias_init(f32x16& p0, f32x16& p1, float base, float nslope2, float nM2, int rel  ) {
;     if (rel <= -63 || rel >= 31) {
;         const float sg = (rel < 0) ? -nslope2 : nslope2, lbv = fmaf(-sg, base, nM2);
; #pragma unroll
;         for (int r = 0; r < 16; ++r) { p0[r] = fmaf((float)((r & 3) + 8 * (r >> 2)), sg, lbv); p1[r] = fmaf((float)((r & 3) + 8 * (r >> 2) + 32), sg, lbv); }
;     } else {
; #pragma unroll
	v_mfma_f32_32x32x16_bf16 v[32:47], v[136:139], v[148:151], v[32:47]
	ds_read_b64_tr_b16 v[148:149], v252 offset:45568
	ds_read_b64_tr_b16 v[150:151], v252 offset:47616
	v_fmamk_f32 v65, v185, 0x42040000, v187
	v_fmamk_f32 v66, v185, 0x42080000, v187
	v_fmamk_f32 v67, v185, 0x420c0000, v187
	v_fmamk_f32 v68, v185, 0x42200000, v187
	v_fmamk_f32 v69, v185, 0x42240000, v187
	s_waitcnt lgkmcnt(6)
	v_mfma_f32_32x32x16_bf16 v[16:31], v[136:139], v[152:155], v[16:31]
	ds_read_b64_tr_b16 v[152:153], v252 offset:46080
	ds_read_b64_tr_b16 v[154:155], v252 offset:48128
	v_fmamk_f32 v70, v185, 0x42280000, v187
	v_fmamk_f32 v71, v185, 0x422c0000, v187
	v_fmamk_f32 v72, v185, 0x42400000, v187
	v_fmamk_f32 v73, v185, 0x42440000, v187
	v_fmamk_f32 v74, v185, 0x42480000, v187
	s_waitcnt lgkmcnt(6)
	v_mfma_f32_32x32x16_bf16 v[0:15], v[136:139], v[156:159], v[0:15]
	ds_read_b64_tr_b16 v[156:157], v252 offset:46592
	ds_read_b64_tr_b16 v[158:159], v252 offset:48640
	v_fmamk_f32 v75, v185, 0x424c0000, v187
	v_fmamk_f32 v76, v185, 0x42600000, v187
	v_fmamk_f32 v77, v185, 0x42640000, v187
	v_fmamk_f32 v78, v185, 0x42680000, v187
	v_fmamk_f32 v79, v185, 0x426c0000, v187
	s_waitcnt lgkmcnt(6)
	v_mfma_f32_32x32x16_bf16 v[48:63], v[140:143], v[144:147], v[48:63]
	ds_read_b64_tr_b16 v[144:145], v252 offset:49152
	ds_read_b64_tr_b16 v[146:147], v252 offset:51200
	v_exp_f32_e32 v112, v112
	v_exp_f32_e32 v113, v113
	v_exp_f32_e32 v114, v114
	v_exp_f32_e32 v115, v115
	v_add_f32_e32 v182, v112, v182
	s_waitcnt lgkmcnt(6)
	v_mfma_f32_32x32x16_bf16 v[32:47], v[140:143], v[148:151], v[32:47]
	ds_read_b64_tr_b16 v[148:149], v252 offset:49664
	ds_read_b64_tr_b16 v[150:151], v252 offset:51712
	v_add_f32_e32 v182, v113, v182
	v_cvt_pk_bf16_f32 v128, v112, v113
	v_exp_f32_e32 v116, v116
	v_exp_f32_e32 v117, v117
	v_add_f32_e32 v182, v114, v182
	s_waitcnt lgkmcnt(6)
	v_mfma_f32_32x32x16_bf16 v[16:31], v[140:143], v[152:155], v[16:31]
	ds_read_b64_tr_b16 v[152:153], v252 offset:50176
	ds_read_b64_tr_b16 v[154:155], v252 offset:52224
	v_add_f32_e32 v182, v115, v182
	v_cvt_pk_bf16_f32 v129, v114, v115
	v_exp_f32_e32 v118, v118
	v_exp_f32_e32 v119, v119
	v_add_f32_e32 v182, v116, v182
	s_waitcnt lgkmcnt(6)
	v_mfma_f32_32x32x16_bf16 v[0:15], v[140:143], v[156:159], v[0:15]
	ds_read_b64_tr_b16 v[156:157], v252 offset:50688
	ds_read_b64_tr_b16 v[158:159], v252 offset:52736
	v_add_f32_e32 v182, v117, v182
	v_cvt_pk_bf16_f32 v130, v116, v117
	v_cvt_pk_bf16_f32 v131, v118, v119
	v_add_f32_e32 v182, v118, v182
	v_add_f32_e32 v182, v119, v182
	s_add_i32 s100, s55, 62
	s_cmp_lt_u32 s100, 93
	s_cbranch_scc0 .Lsym_nodiag_s2
	v_add_f32_e32 v190, 0x00000000, v183
	v_add_f32_e32 v191, 0xc2000000, v183
	v_fma_f32 v80, |v190|, v186, s16
	v_fma_f32 v64, |v191|, v186, s16
	v_add_f32_e32 v190, 0xbf800000, v183
	v_add_f32_e32 v191, 0xc2040000, v183
	v_fma_f32 v81, |v190|, v186, s16
	v_fma_f32 v65, |v191|, v186, s16
	v_add_f32_e32 v190, 0xc0000000, v183
	v_add_f32_e32 v191, 0xc2080000, v183
	v_fma_f32 v82, |v190|, v186, s16
	v_fma_f32 v66, |v191|, v186, s16
	v_add_f32_e32 v190, 0xc0400000, v183
	v_add_f32_e32 v191, 0xc20c0000, v183
	v_fma_f32 v83, |v190|, v186, s16
	v_fma_f32 v67, |v191|, v186, s16
	v_add_f32_e32 v190, 0xc1000000, v183
	v_add_f32_e32 v191, 0xc2200000, v183
	v_fma_f32 v84, |v190|, v186, s16
	v_fma_f32 v68, |v191|, v186, s16
	v_add_f32_e32 v190, 0xc1100000, v183
	v_add_f32_e32 v191, 0xc2240000, v183
	v_fma_f32 v85, |v190|, v186, s16
	v_fma_f32 v69, |v191|, v186, s16
	v_add_f32_e32 v190, 0xc1200000, v183
	v_add_f32_e32 v191, 0xc2280000, v183
	v_fma_f32 v86, |v190|, v186, s16
	v_fma_f32 v70, |v191|, v186, s16
	v_add_f32_e32 v190, 0xc1300000, v183
	v_add_f32_e32 v191, 0xc22c0000, v183
	v_fma_f32 v87, |v190|, v186, s16
	v_fma_f32 v71, |v191|, v186, s16
	v_add_f32_e32 v190, 0xc1800000, v183
	v_add_f32_e32 v191, 0xc2400000, v183
	v_fma_f32 v88, |v190|, v186, s16
	v_fma_f32 v72, |v191|, v186, s16
	v_add_f32_e32 v190, 0xc1880000, v183
	v_add_f32_e32 v191, 0xc2440000, v183
	v_fma_f32 v89, |v190|, v186, s16
	v_fma_f32 v73, |v191|, v186, s16
	v_add_f32_e32 v190, 0xc1900000, v183
	v_add_f32_e32 v191, 0xc2480000, v183
	v_fma_f32 v90, |v190|, v186, s16
	v_fma_f32 v74, |v191|, v186, s16
	v_add_f32_e32 v190, 0xc1980000, v183
	v_add_f32_e32 v191, 0xc24c0000, v183
	v_fma_f32 v91, |v190|, v186, s16
	v_fma_f32 v75, |v191|, v186, s16
	v_add_f32_e32 v190, 0xc1c00000, v183
	v_add_f32_e32 v191, 0xc2600000, v183
	v_fma_f32 v92, |v190|, v186, s16
	v_fma_f32 v76, |v191|, v186, s16
	v_add_f32_e32 v190, 0xc1c80000, v183
	v_add_f32_e32 v191, 0xc2640000, v183
	v_fma_f32 v93, |v190|, v186, s16
	v_fma_f32 v77, |v191|, v186, s16
	v_add_f32_e32 v190, 0xc1d00000, v183
	v_add_f32_e32 v191, 0xc2680000, v183
	v_fma_f32 v94, |v190|, v186, s16
	v_fma_f32 v78, |v191|, v186, s16
	v_add_f32_e32 v190, 0xc1d80000, v183
	v_add_f32_e32 v191, 0xc26c0000, v183
	v_fma_f32 v95, |v190|, v186, s16
	v_fma_f32 v79, |v191|, v186, s16

; #define SBAR() __builtin_amdgcn_sched_barrier(0)
; #define PK4(P, BASE, OUT) do { u32x4 w = {cvtpk(P[BASE + 0], P[BASE + 1]), cvtpk(P[BASE + 2], P[BASE + 3]), cvtpk(P[BASE + 4], P[BASE + 5]), cvtpk(P[BASE + 6], P[BASE + 7])}; \
;     OUT = *reinterpret_cast<bf16x8*>(&w); } while (0)
; template <int KS> __device__ __forceinline__ void pv_ks(f32x16* o, int vb, bf16x8 pa) {
;     const s16x4 l0 = tr_read<v_rd_off(0, KS, 0)>(vb), h0 = tr_read<v_rd_off(0, KS, 1)>(vb), l1 = tr_read<v_rd_off(1, KS, 0)>(vb), h1 = tr_read<v_rd_off(1, KS, 1)>(vb);
;     const s16x4 l2 = tr_read<v_rd_off(2, KS, 0)>(vb), h2 = tr_read<v_rd_off(2, KS, 1)>(vb), l3 = tr_read<v_rd_off(3, KS, 0)>(vb), h3 = tr_read<v_rd_off(3, KS, 1)>(vb);
;     ...
;     asm volatile("s_waitcnt lgkmcnt(6)" ::: "memory"); SBAR();
;     o[0] = __builtin_amdgcn_mfma_f32_32x32x16_bf16(pa, PK(l0, h0), o[0], 0, 0, 0);
;     asm volatile("s_waitcnt lgkmcnt(4)" ::: "memory"); SBAR();
;     o[1] = __builtin_amdgcn_mfma_f32_32x32x16_bf16(pa, PK(l1, h1), o[1], 0, 0, 0);
;     asm volatile("s_waitcnt lgkmcnt(2)" ::: "memory"); SBAR();
;     o[2] = __builtin_amdgcn_mfma_f32_32x32x16_bf16(pa, PK(l2, h2), o[2], 0, 0, 0);
;     asm volatile("s_waitcnt lgkmcnt(0)" ::: "memory"); SBAR();
;     o[3] = __builtin_amdgcn_mfma_f32_32x32x16_bf16(pa, PK(l3, h3), o[3], 0, 0, 0);
;     ...
; }
; __device__ __forceinline__ void pv_d0(f32x16* o, int vb, bf16x8 pa0, bf16x8 pa1, bf16x8 pa2, bf16x8 pa3) {
;     __builtin_amdgcn_s_setprio(1);
;     pv_ks<0>(o, vb, pa0); pv_ks<1>(o, vb, pa1); pv_ks<2>(o, vb, pa2); pv_ks<3>(o, vb, pa3);
;     __builtin_amdgcn_s_setprio(0);
; }
; __device__ __forceinline__ void exp_half(f32x16& p) {
; #pragma unroll
;     for (int r = 0; r < 16; ++r) p[r] = __builtin_amdgcn_exp2f(p[r]);
; }
; __device__ __forceinline__ void pack_p(const f32x16& p0, const f32x16& p1, float& l_reg, bf16x8& pa0, bf16x8& pa1, bf16x8& pa2, bf16x8& pa3) {
;     float ps = 0;
; #pragma unroll
;     for (int r = 0; r < 16; ++r) ps += p0[r];
; #pragma unroll
;     for (int r = 0; r < 16; ++r) ps += p1[r];
;     l_reg += ps;
;     ...
;     PK4(p0, 0, pa0); PK4(p0, 8, pa1); PK4(p1, 0, pa2); PK4(p1, 8, pa3);
;     ...
; }
.Lsym_nostage_s3:
	s_waitcnt lgkmcnt(14)
	v_mfma_f32_32x32x16_bf16 v[48:63], v[128:131], v[144:147], v[48:63]
	ds_read_b64_tr_b16 v[144:145], v252 offset:53248
	ds_read_b64_tr_b16 v[146:147], v252 offset:55296
	v_exp_f32_e32 v120, v120
	v_exp_f32_e32 v121, v121
	v_exp_f32_e32 v122, v122
	v_exp_f32_e32 v123, v123
	v_add_f32_e32 v182, v120, v182
	s_waitcnt lgkmcnt(9)
	v_mfma_f32_32x32x16_bf16 v[80:95], v[192:195], v[172:175], v[80:95]
	v_add_f32_e32 v182, v121, v182
	v_cvt_pk_bf16_f32 v132, v120, v121
	v_exp_f32_e32 v124, v124
	v_exp_f32_e32 v125, v125
	v_mfma_f32_32x32x16_bf16 v[32:47], v[128:131], v[148:151], v[32:47]
	ds_read_b64_tr_b16 v[148:149], v252 offset:53760
	ds_read_b64_tr_b16 v[150:151], v252 offset:55808
	v_add_f32_e32 v182, v122, v182
	v_add_f32_e32 v182, v123, v182
	v_cvt_pk_bf16_f32 v133, v122, v123
	v_exp_f32_e32 v126, v126
	v_exp_f32_e32 v127, v127
	s_waitcnt lgkmcnt(10)
	v_mfma_f32_32x32x16_bf16 v[64:79], v[196:199], v[172:175], v[64:79]
	v_add_f32_e32 v182, v124, v182
	v_add_f32_e32 v182, v125, v182
	v_cvt_pk_bf16_f32 v134, v124, v125
	v_cvt_pk_bf16_f32 v135, v126, v127
	v_mfma_f32_32x32x16_bf16 v[16:31], v[128:131], v[152:155], v[16:31]
	ds_read_b64_tr_b16 v[152:153], v252 offset:54272
	ds_read_b64_tr_b16 v[154:155], v252 offset:56320
	v_add_f32_e32 v182, v126, v182
	v_add_f32_e32 v182, v127, v182
	v_exp_f32_e32 v96, v96
	v_exp_f32_e32 v97, v97
	v_exp_f32_e32 v98, v98
	s_waitcnt lgkmcnt(11)
	v_mfma_f32_32x32x16_bf16 v[80:95], v[200:203], v[168:171], v[80:95]
	v_exp_f32_e32 v99, v99
	v_add_f32_e32 v182, v96, v182
	v_add_f32_e32 v182, v97, v182
	v_cvt_pk_bf16_f32 v136, v96, v97
	v_mfma_f32_32x32x16_bf16 v[0:15], v[128:131], v[156:159], v[0:15]
	ds_read_b64_tr_b16 v[156:157], v252 offset:54784
	ds_read_b64_tr_b16 v[158:159], v252 offset:56832
	v_exp_f32_e32 v100, v100
	v_exp_f32_e32 v101, v101
	v_add_f32_e32 v182, v98, v182
	v_add_f32_e32 v182, v99, v182
	v_cvt_pk_bf16_f32 v137, v98, v99
	s_waitcnt lgkmcnt(12)
	v_mfma_f32_32x32x16_bf16 v[64:79], v[204:207], v[168:171], v[64:79]
	v_exp_f32_e32 v102, v102
	v_exp_f32_e32 v103, v103
	v_add_f32_e32 v182, v100, v182
	v_add_f32_e32 v182, v101, v182
	s_waitcnt lgkmcnt(6)
	v_mfma_f32_32x32x16_bf16 v[48:63], v[132:135], v[144:147], v[48:63]
	ds_read_b64_tr_b16 v[144:145], v252 offset:57344
	ds_read_b64_tr_b16 v[146:147], v252 offset:59392
	v_cvt_pk_bf16_f32 v138, v100, v101
	v_cvt_pk_bf16_f32 v139, v102, v103
	v_add_f32_e32 v182, v102, v182
	v_add_f32_e32 v182, v103, v182
	v_exp_f32_e32 v104, v104
	v_mfma_f32_32x32x16_bf16 v[80:95], v[208:211], v[164:167], v[80:95]
	v_exp_f32_e32 v105, v105
	v_exp_f32_e32 v106, v106
	v_exp_f32_e32 v107, v107
	v_add_f32_e32 v182, v104, v182
	v_add_f32_e32 v182, v105, v182
	s_waitcnt lgkmcnt(6)
	v_mfma_f32_32x32x16_bf16 v[32:47], v[132:135], v[148:151], v[32:47]
	ds_read_b64_tr_b16 v[148:149], v252 offset:57856
	ds_read_b64_tr_b16 v[150:151], v252 offset:59904
	v_cvt_pk_bf16_f32 v140, v104, v105
	v_exp_f32_e32 v108, v108
	v_exp_f32_e32 v109, v109
	v_add_f32_e32 v182, v106, v182
	v_add_f32_e32 v182, v107, v182
	v_mfma_f32_32x32x16_bf16 v[64:79], v[212:215], v[164:167], v[64:79]
	v_cvt_pk_bf16_f32 v141, v106, v107
	v_exp_f32_e32 v110, v110
	v_exp_f32_e32 v111, v111
	v_add_f32_e32 v182, v108, v182
	v_add_f32_e32 v182, v109, v182
	s_waitcnt lgkmcnt(6)
	v_mfma_f32_32x32x16_bf16 v[16:31], v[132:135], v[152:155], v[16:31]
	ds_read_b64_tr_b16 v[152:153], v252 offset:58368
	ds_read_b64_tr_b16 v[154:155], v252 offset:60416
	v_cvt_pk_bf16_f32 v142, v108, v109
	v_cvt_pk_bf16_f32 v143, v110, v111
	v_add_f32_e32 v182, v110, v182
	v_add_f32_e32 v182, v111, v182
	s_cmp_lt_i32 s55, 0
	v_mfma_f32_32x32x16_bf16 v[80:95], v[216:219], v[160:163], v[80:95]
	s_cselect_b32 s100, -1.0, 1.0
	v_mul_f32_e32 v185, s100, v186
	v_fma_f32 v187, -v185, v183, s16
	v_fmamk_f32 v112, v185, 0x00000000, v187
	v_fmamk_f32 v113, v185, 0x3f800000, v187
	s_waitcnt lgkmcnt(6)
	v_mfma_f32_32x32x16_bf16 v[0:15], v[132:135], v[156:159], v[0:15]
	ds_read_b64_tr_b16 v[156:157], v252 offset:58880
	ds_read_b64_tr_b16 v[158:159], v252 offset:60928
	v_fmamk_f32 v114, v185, 0x40000000, v187
	v_fmamk_f32 v115, v185, 0x40400000, v187
	v_fmamk_f32 v116, v185, 0x41000000, v187
	v_fmamk_f32 v117, v185, 0x41100000, v187
	v_fmamk_f32 v118, v185, 0x41200000, v187
	v_mfma_f32_32x32x16_bf16 v[64:79], v[220:223], v[160:163], v[64:79]
	v_fmamk_f32 v119, v185, 0x41300000, v187
	v_fmamk_f32 v120, v185, 0x41800000, v187
	v_fmamk_f32 v121, v185, 0x41880000, v187
	v_fmamk_f32 v122, v185, 0x41900000, v187
	v_fmamk_f32 v123, v185, 0x41980000, v187
	s_waitcnt lgkmcnt(6)
	v_mfma_f32_32x32x16_bf16 v[48:63], v[136:139], v[144:147], v[48:63]
	ds_read_b64_tr_b16 v[144:145], v252 offset:61440
	ds_read_b64_tr_b16 v[146:147], v252 offset:63488
	v_fmamk_f32 v124, v185, 0x41c00000, v187
	v_fmamk_f32 v125, v185, 0x41c80000, v187
	v_fmamk_f32 v126, v185, 0x41d00000, v187
	v_fmamk_f32 v127, v185, 0x41d80000, v187
	v_fmamk_f32 v96, v185, 0x42000000, v187
	s_waitcnt lgkmcnt(6)
; #define SBAR() __builtin_amdgcn_sched_barrier(0)
; template <int KS> __device__ __forceinline__ void pv_ks(f32x16* o, int vb, bf16x8 pa) {
;     const s16x4 l0 = tr_read<v_rd_off(0, KS, 0)>(vb), h0 = tr_read<v_rd_off(0, KS, 1)>(vb), l1 = tr_read<v_rd_off(1, KS, 0)>(vb), h1 = tr_read<v_rd_off(1, KS, 1)>(vb);
;     const s16x4 l2 = tr_read<v_rd_off(2, KS, 0)>(vb), h2 = tr_read<v_rd_off(2, KS, 1)>(vb), l3 = tr_read<v_rd_off(3, KS, 0)>(vb), h3 = tr_read<v_rd_off(3, KS, 1)>(vb);
;     ...
;     asm volatile("s_waitcnt lgkmcnt(6)" ::: "memory"); SBAR();
;     o[0] = __builtin_amdgcn_mfma_f32_32x32x16_bf16(pa, PK(l0, h0), o[0], 0, 0, 0);
;     asm volatile("s_waitcnt lgkmcnt(4)" ::: "memory"); SBAR();
;     o[1] = __builtin_amdgcn_mfma_f32_32x32x16_bf16(pa, PK(l1, h1), o[1], 0, 0, 0);
;     asm volatile("s_waitcnt lgkmcnt(2)" ::: "memory"); SBAR();
;     o[2] = __builtin_amdgcn_mfma_f32_32x32x16_bf16(pa, PK(l2, h2), o[2], 0, 0, 0);
;     asm volatile("s_waitcnt lgkmcnt(0)" ::: "memory"); SBAR();
;     o[3] = __builtin_amdgcn_mfma_f32_32x32x16_bf16(pa, PK(l3, h3), o[3], 0, 0, 0);
;     ...
; }
; __device__ __forceinline__ void pv_d0(f32x16* o, int vb, bf16x8 pa0, bf16x8 pa1, bf16x8 pa2, bf16x8 pa3) {
;     __builtin_amdgcn_s_setprio(1);
;     pv_ks<0>(o, vb, pa0); pv_ks<1>(o, vb, pa1); pv_ks<2>(o, vb, pa2); pv_ks<3>(o, vb, pa3);
;     __builtin_amdgcn_s_setprio(0);
; }
; __device__ __forceinline__ void exp_half(f32x16& p) {
; #pragma unroll
;     for (int r = 0; r < 16; ++r) p[r] = __builtin_amdgcn_exp2f(p[r]);
; }
; __device__ __forceinline__ void pack_p(const f32x16& p0, const f32x16& p1, float& l_reg, bf16x8& pa0, bf16x8& pa1, bf16x8& pa2, bf16x8& pa3) {
;     float ps = 0;
; #pragma unroll
;     for (int r = 0; r < 16; ++r) ps += p0[r];
; #pragma unroll
;     for (int r = 0; r < 16; ++r) ps += p1[r];
;     l_reg += ps;
;     ...
;     PK4(p0, 0, pa0); PK4(p0, 8, pa1); PK4(p1, 0, pa2); PK4(p1, 8, pa3);
;     ...
; }
; __device__ __forceinline__ void bias_init(f32x16& p0, f32x16& p1, float base, float nslope2, float nM2, int rel  ) {
;     if (rel <= -63 || rel >= 31) {
;         const float sg = (rel < 0) ? -nslope2 : nslope2, lbv = fmaf(-sg, base, nM2);
; #pragma unroll
;         for (int r = 0; r < 16; ++r) { p0[r] = fmaf((float)((r & 3) + 8 * (r >> 2)), sg, lbv); p1[r] = fmaf((float)((r & 3) + 8 * (r >> 2) + 32), sg, lbv); }
;     } else {
; #pragma unroll
	v_mfma_f32_32x32x16_bf16 v[32:47], v[136:139], v[148:151], v[32:47]
	ds_read_b64_tr_b16 v[148:149], v252 offset:61952
	ds_read_b64_tr_b16 v[150:151], v252 offset:64000
	v_fmamk_f32 v97, v185, 0x42040000, v187
	v_fmamk_f32 v98, v185, 0x42080000, v187
	v_fmamk_f32 v99, v185, 0x420c0000, v187
	v_fmamk_f32 v100, v185, 0x42200000, v187
	v_fmamk_f32 v101, v185, 0x42240000, v187
	s_waitcnt lgkmcnt(6)
	v_mfma_f32_32x32x16_bf16 v[16:31], v[136:139], v[152:155], v[16:31]
	ds_read_b64_tr_b16 v[152:153], v252 offset:62464
	ds_read_b64_tr_b16 v[154:155], v252 offset:64512
	v_fmamk_f32 v102, v185, 0x42280000, v187
	v_fmamk_f32 v103, v185, 0x422c0000, v187
	v_fmamk_f32 v104, v185, 0x42400000, v187
	v_fmamk_f32 v105, v185, 0x42440000, v187
	v_fmamk_f32 v106, v185, 0x42480000, v187
	s_waitcnt lgkmcnt(6)
	v_mfma_f32_32x32x16_bf16 v[0:15], v[136:139], v[156:159], v[0:15]
	ds_read_b64_tr_b16 v[156:157], v252 offset:62976
	ds_read_b64_tr_b16 v[158:159], v252 offset:65024
	v_fmamk_f32 v107, v185, 0x424c0000, v187
	v_fmamk_f32 v108, v185, 0x42600000, v187
	v_fmamk_f32 v109, v185, 0x42640000, v187
	v_fmamk_f32 v110, v185, 0x42680000, v187
	v_fmamk_f32 v111, v185, 0x426c0000, v187
	s_waitcnt lgkmcnt(6)
	v_mfma_f32_32x32x16_bf16 v[48:63], v[140:143], v[144:147], v[48:63]
	ds_read_b64_tr_b16 v[144:145], v252 offset:0
	ds_read_b64_tr_b16 v[146:147], v252 offset:2048
	v_exp_f32_e32 v80, v80
	v_exp_f32_e32 v81, v81
	v_exp_f32_e32 v82, v82
	v_exp_f32_e32 v83, v83
	v_add_f32_e32 v182, v80, v182
	s_waitcnt lgkmcnt(6)
	v_mfma_f32_32x32x16_bf16 v[32:47], v[140:143], v[148:151], v[32:47]
	ds_read_b64_tr_b16 v[148:149], v252 offset:512
	ds_read_b64_tr_b16 v[150:151], v252 offset:2560
	v_add_f32_e32 v182, v81, v182
	v_cvt_pk_bf16_f32 v128, v80, v81
	v_exp_f32_e32 v84, v84
	v_exp_f32_e32 v85, v85
	v_add_f32_e32 v182, v82, v182
	s_waitcnt lgkmcnt(6)
	v_mfma_f32_32x32x16_bf16 v[16:31], v[140:143], v[152:155], v[16:31]
	ds_read_b64_tr_b16 v[152:153], v252 offset:1024
	ds_read_b64_tr_b16 v[154:155], v252 offset:3072
	v_add_f32_e32 v182, v83, v182
	v_cvt_pk_bf16_f32 v129, v82, v83
	v_exp_f32_e32 v86, v86
	v_exp_f32_e32 v87, v87
	v_add_f32_e32 v182, v84, v182
	s_waitcnt lgkmcnt(6)
	v_mfma_f32_32x32x16_bf16 v[0:15], v[140:143], v[156:159], v[0:15]
	ds_read_b64_tr_b16 v[156:157], v252 offset:1536
	ds_read_b64_tr_b16 v[158:159], v252 offset:3584
	v_add_f32_e32 v182, v85, v182
	v_cvt_pk_bf16_f32 v130, v84, v85
	v_cvt_pk_bf16_f32 v131, v86, v87
	v_add_f32_e32 v182, v86, v182
	v_add_f32_e32 v182, v87, v182
	s_add_i32 s100, s55, 62
	s_cmp_lt_u32 s100, 93
	s_cbranch_scc0 .Lsym_nodiag_s3
	v_add_f32_e32 v190, 0x00000000, v183
	v_add_f32_e32 v191, 0xc2000000, v183
	v_fma_f32 v112, |v190|, v186, s16
	v_fma_f32 v96, |v191|, v186, s16
	v_add_f32_e32 v190, 0xbf800000, v183
	v_add_f32_e32 v191, 0xc2040000, v183
	v_fma_f32 v113, |v190|, v186, s16
	v_fma_f32 v97, |v191|, v186, s16
	v_add_f32_e32 v190, 0xc0000000, v183
	v_add_f32_e32 v191, 0xc2080000, v183
	v_fma_f32 v114, |v190|, v186, s16
	v_fma_f32 v98, |v191|, v186, s16
	v_add_f32_e32 v190, 0xc0400000, v183
	v_add_f32_e32 v191, 0xc20c0000, v183
	v_fma_f32 v115, |v190|, v186, s16
	v_fma_f32 v99, |v191|, v186, s16
	v_add_f32_e32 v190, 0xc1000000, v183
	v_add_f32_e32 v191, 0xc2200000, v183
	v_fma_f32 v116, |v190|, v186, s16
	v_fma_f32 v100, |v191|, v186, s16
	v_add_f32_e32 v190, 0xc1100000, v183
	v_add_f32_e32 v191, 0xc2240000, v183
	v_fma_f32 v117, |v190|, v186, s16
	v_fma_f32 v101, |v191|, v186, s16
	v_add_f32_e32 v190, 0xc1200000, v183
	v_add_f32_e32 v191, 0xc2280000, v183
	v_fma_f32 v118, |v190|, v186, s16
	v_fma_f32 v102, |v191|, v186, s16
	v_add_f32_e32 v190, 0xc1300000, v183
	v_add_f32_e32 v191, 0xc22c0000, v183
	v_fma_f32 v119, |v190|, v186, s16
	v_fma_f32 v103, |v191|, v186, s16
	v_add_f32_e32 v190, 0xc1800000, v183
	v_add_f32_e32 v191, 0xc2400000, v183
	v_fma_f32 v120, |v190|, v186, s16
	v_fma_f32 v104, |v191|, v186, s16
	v_add_f32_e32 v190, 0xc1880000, v183
	v_add_f32_e32 v191, 0xc2440000, v183
	v_fma_f32 v121, |v190|, v186, s16
	v_fma_f32 v105, |v191|, v186, s16
	v_add_f32_e32 v190, 0xc1900000, v183
	v_add_f32_e32 v191, 0xc2480000, v183
	v_fma_f32 v122, |v190|, v186, s16
	v_fma_f32 v106, |v191|, v186, s16
	v_add_f32_e32 v190, 0xc1980000, v183
	v_add_f32_e32 v191, 0xc24c0000, v183
	v_fma_f32 v123, |v190|, v186, s16
	v_fma_f32 v107, |v191|, v186, s16
	v_add_f32_e32 v190, 0xc1c00000, v183
	v_add_f32_e32 v191, 0xc2600000, v183
	v_fma_f32 v124, |v190|, v186, s16
	v_fma_f32 v108, |v191|, v186, s16
	v_add_f32_e32 v190, 0xc1c80000, v183
	v_add_f32_e32 v191, 0xc2640000, v183
	v_fma_f32 v125, |v190|, v186, s16
	v_fma_f32 v109, |v191|, v186, s16
	v_add_f32_e32 v190, 0xc1d00000, v183
	v_add_f32_e32 v191, 0xc2680000, v183
	v_fma_f32 v126, |v190|, v186, s16
	v_fma_f32 v110, |v191|, v186, s16
	v_add_f32_e32 v190, 0xc1d80000, v183
	v_add_f32_e32 v191, 0xc26c0000, v183
	v_fma_f32 v127, |v190|, v186, s16
	v_fma_f32 v111, |v191|, v186, s16

; #define SBAR() __builtin_amdgcn_sched_barrier(0)
; #define PK4(P, BASE, OUT) do { u32x4 w = {cvtpk(P[BASE + 0], P[BASE + 1]), cvtpk(P[BASE + 2], P[BASE + 3]), cvtpk(P[BASE + 4], P[BASE + 5]), cvtpk(P[BASE + 6], P[BASE + 7])}; \
;     OUT = *reinterpret_cast<bf16x8*>(&w); } while (0)
; template <int KS> __device__ __forceinline__ void pv_ks(f32x16* o, int vb, bf16x8 pa) {
;     const s16x4 l0 = tr_read<v_rd_off(0, KS, 0)>(vb), h0 = tr_read<v_rd_off(0, KS, 1)>(vb), l1 = tr_read<v_rd_off(1, KS, 0)>(vb), h1 = tr_read<v_rd_off(1, KS, 1)>(vb);
;     const s16x4 l2 = tr_read<v_rd_off(2, KS, 0)>(vb), h2 = tr_read<v_rd_off(2, KS, 1)>(vb), l3 = tr_read<v_rd_off(3, KS, 0)>(vb), h3 = tr_read<v_rd_off(3, KS, 1)>(vb);
;     ...
;     asm volatile("s_waitcnt lgkmcnt(6)" ::: "memory"); SBAR();
;     o[0] = __builtin_amdgcn_mfma_f32_32x32x16_bf16(pa, PK(l0, h0), o[0], 0, 0, 0);
;     asm volatile("s_waitcnt lgkmcnt(4)" ::: "memory"); SBAR();
;     o[1] = __builtin_amdgcn_mfma_f32_32x32x16_bf16(pa, PK(l1, h1), o[1], 0, 0, 0);
;     asm volatile("s_waitcnt lgkmcnt(2)" ::: "memory"); SBAR();
;     o[2] = __builtin_amdgcn_mfma_f32_32x32x16_bf16(pa, PK(l2, h2), o[2], 0, 0, 0);
;     asm volatile("s_waitcnt lgkmcnt(0)" ::: "memory"); SBAR();
;     o[3] = __builtin_amdgcn_mfma_f32_32x32x16_bf16(pa, PK(l3, h3), o[3], 0, 0, 0);
;     ...
; }
; __device__ __forceinline__ void pv_d0(f32x16* o, int vb, bf16x8 pa0, bf16x8 pa1, bf16x8 pa2, bf16x8 pa3) {
;     __builtin_amdgcn_s_setprio(1);
;     pv_ks<0>(o, vb, pa0); pv_ks<1>(o, vb, pa1); pv_ks<2>(o, vb, pa2); pv_ks<3>(o, vb, pa3);
;     __builtin_amdgcn_s_setprio(0);
; }
; __device__ __forceinline__ void exp_half(f32x16& p) {
; #pragma unroll
;     for (int r = 0; r < 16; ++r) p[r] = __builtin_amdgcn_exp2f(p[r]);
; }
; __device__ __forceinline__ void pack_p(const f32x16& p0, const f32x16& p1, float& l_reg, bf16x8& pa0, bf16x8& pa1, bf16x8& pa2, bf16x8& pa3) {
;     float ps = 0;
; #pragma unroll
;     for (int r = 0; r < 16; ++r) ps += p0[r];
; #pragma unroll
;     for (int r = 0; r < 16; ++r) ps += p1[r];
;     l_reg += ps;
;     ...
;     PK4(p0, 0, pa0); PK4(p0, 8, pa1); PK4(p1, 0, pa2); PK4(p1, 8, pa3);
;     ...
; }
.Lsym_last1:
	s_waitcnt vmcnt(0)
	s_barrier
	s_waitcnt lgkmcnt(6)
	v_mfma_f32_32x32x16_bf16 v[48:63], v[128:131], v[144:147], v[48:63]
	ds_read_b64_tr_b16 v[144:145], v252 offset:20480
	ds_read_b64_tr_b16 v[146:147], v252 offset:22528
	v_exp_f32_e32 v120, v120
	v_exp_f32_e32 v121, v121
	s_waitcnt lgkmcnt(6)
	v_mfma_f32_32x32x16_bf16 v[32:47], v[128:131], v[148:151], v[32:47]
	ds_read_b64_tr_b16 v[148:149], v252 offset:20992
	ds_read_b64_tr_b16 v[150:151], v252 offset:23040
	v_exp_f32_e32 v122, v122
	v_exp_f32_e32 v123, v123
	v_add_f32_e32 v182, v120, v182
	v_add_f32_e32 v182, v121, v182
	v_cvt_pk_bf16_f32 v132, v120, v121
	s_waitcnt lgkmcnt(6)
	v_mfma_f32_32x32x16_bf16 v[16:31], v[128:131], v[152:155], v[16:31]
	ds_read_b64_tr_b16 v[152:153], v252 offset:21504
	ds_read_b64_tr_b16 v[154:155], v252 offset:23552
	v_exp_f32_e32 v124, v124
	v_exp_f32_e32 v125, v125
	v_add_f32_e32 v182, v122, v182
	v_add_f32_e32 v182, v123, v182
	v_cvt_pk_bf16_f32 v133, v122, v123
	s_waitcnt lgkmcnt(6)
	v_mfma_f32_32x32x16_bf16 v[0:15], v[128:131], v[156:159], v[0:15]
	ds_read_b64_tr_b16 v[156:157], v252 offset:22016
	ds_read_b64_tr_b16 v[158:159], v252 offset:24064
	v_exp_f32_e32 v126, v126
	v_exp_f32_e32 v127, v127
	v_add_f32_e32 v182, v124, v182
	v_add_f32_e32 v182, v125, v182
	v_cvt_pk_bf16_f32 v134, v124, v125
	v_cvt_pk_bf16_f32 v135, v126, v127
	v_add_f32_e32 v182, v126, v182
	v_add_f32_e32 v182, v127, v182
	s_waitcnt lgkmcnt(6)
	v_mfma_f32_32x32x16_bf16 v[48:63], v[132:135], v[144:147], v[48:63]
	ds_read_b64_tr_b16 v[144:145], v252 offset:24576
	ds_read_b64_tr_b16 v[146:147], v252 offset:26624
	v_exp_f32_e32 v96, v96
	v_exp_f32_e32 v97, v97
	s_waitcnt lgkmcnt(6)
	v_mfma_f32_32x32x16_bf16 v[32:47], v[132:135], v[148:151], v[32:47]
	ds_read_b64_tr_b16 v[148:149], v252 offset:25088
	ds_read_b64_tr_b16 v[150:151], v252 offset:27136
	v_exp_f32_e32 v98, v98
	v_exp_f32_e32 v99, v99
	v_add_f32_e32 v182, v96, v182
	v_add_f32_e32 v182, v97, v182
	v_cvt_pk_bf16_f32 v136, v96, v97
	s_waitcnt lgkmcnt(6)
	v_mfma_f32_32x32x16_bf16 v[16:31], v[132:135], v[152:155], v[16:31]
	ds_read_b64_tr_b16 v[152:153], v252 offset:25600
	ds_read_b64_tr_b16 v[154:155], v252 offset:27648
	v_exp_f32_e32 v100, v100
	v_exp_f32_e32 v101, v101
	v_add_f32_e32 v182, v98, v182
	v_add_f32_e32 v182, v99, v182
	v_cvt_pk_bf16_f32 v137, v98, v99
	s_waitcnt lgkmcnt(6)
	v_mfma_f32_32x32x16_bf16 v[0:15], v[132:135], v[156:159], v[0:15]
	ds_read_b64_tr_b16 v[156:157], v252 offset:26112
	ds_read_b64_tr_b16 v[158:159], v252 offset:28160
	v_exp_f32_e32 v102, v102
	v_exp_f32_e32 v103, v103
	v_add_f32_e32 v182, v100, v182
	v_add_f32_e32 v182, v101, v182
	v_cvt_pk_bf16_f32 v138, v100, v101
	v_cvt_pk_bf16_f32 v139, v102, v103
	v_add_f32_e32 v182, v102, v182
	v_add_f32_e32 v182, v103, v182
	s_waitcnt lgkmcnt(6)
	v_mfma_f32_32x32x16_bf16 v[48:63], v[136:139], v[144:147], v[48:63]
	ds_read_b64_tr_b16 v[144:145], v252 offset:28672
	ds_read_b64_tr_b16 v[146:147], v252 offset:30720
	v_exp_f32_e32 v104, v104
	v_exp_f32_e32 v105, v105
	s_waitcnt lgkmcnt(6)
	v_mfma_f32_32x32x16_bf16 v[32:47], v[136:139], v[148:151], v[32:47]
	ds_read_b64_tr_b16 v[148:149], v252 offset:29184
	ds_read_b64_tr_b16 v[150:151], v252 offset:31232
	v_exp_f32_e32 v106, v106
	v_exp_f32_e32 v107, v107
	v_add_f32_e32 v182, v104, v182
	v_add_f32_e32 v182, v105, v182
	v_cvt_pk_bf16_f32 v140, v104, v105
	s_waitcnt lgkmcnt(6)
	v_mfma_f32_32x32x16_bf16 v[16:31], v[136:139], v[152:155], v[16:31]
	ds_read_b64_tr_b16 v[152:153], v252 offset:29696
	ds_read_b64_tr_b16 v[154:155], v252 offset:31744
	v_exp_f32_e32 v108, v108
	v_exp_f32_e32 v109, v109
	v_add_f32_e32 v182, v106, v182
	v_add_f32_e32 v182, v107, v182
	v_cvt_pk_bf16_f32 v141, v106, v107
	s_waitcnt lgkmcnt(6)
	v_mfma_f32_32x32x16_bf16 v[0:15], v[136:139], v[156:159], v[0:15]
	ds_read_b64_tr_b16 v[156:157], v252 offset:30208
	ds_read_b64_tr_b16 v[158:159], v252 offset:32256
	v_exp_f32_e32 v110, v110
	v_exp_f32_e32 v111, v111
	v_add_f32_e32 v182, v108, v182
	v_add_f32_e32 v182, v109, v182
	v_cvt_pk_bf16_f32 v142, v108, v109
	v_cvt_pk_bf16_f32 v143, v110, v111
	v_add_f32_e32 v182, v110, v182
	v_add_f32_e32 v182, v111, v182
	s_waitcnt lgkmcnt(6)
	v_mfma_f32_32x32x16_bf16 v[48:63], v[140:143], v[144:147], v[48:63]
	s_waitcnt lgkmcnt(4)
	v_mfma_f32_32x32x16_bf16 v[32:47], v[140:143], v[148:151], v[32:47]
	s_waitcnt lgkmcnt(2)
	v_mfma_f32_32x32x16_bf16 v[16:31], v[140:143], v[152:155], v[16:31]
	s_waitcnt lgkmcnt(0)
	v_mfma_f32_32x32x16_bf16 v[0:15], v[140:143], v[156:159], v[0:15]
	s_branch .Lsym_done
; #define SBAR() __builtin_amdgcn_sched_barrier(0)
; #define PK4(P, BASE, OUT) do { u32x4 w = {cvtpk(P[BASE + 0], P[BASE + 1]), cvtpk(P[BASE + 2], P[BASE + 3]), cvtpk(P[BASE + 4], P[BASE + 5]), cvtpk(P[BASE + 6], P[BASE + 7])}; \
;     OUT = *reinterpret_cast<bf16x8*>(&w); } while (0)
; template <int KS> __device__ __forceinline__ void pv_ks(f32x16* o, int vb, bf16x8 pa) {
;     const s16x4 l0 = tr_read<v_rd_off(0, KS, 0)>(vb), h0 = tr_read<v_rd_off(0, KS, 1)>(vb), l1 = tr_read<v_rd_off(1, KS, 0)>(vb), h1 = tr_read<v_rd_off(1, KS, 1)>(vb);
;     const s16x4 l2 = tr_read<v_rd_off(2, KS, 0)>(vb), h2 = tr_read<v_rd_off(2, KS, 1)>(vb), l3 = tr_read<v_rd_off(3, KS, 0)>(vb), h3 = tr_read<v_rd_off(3, KS, 1)>(vb);
;     ...
;     asm volatile("s_waitcnt lgkmcnt(6)" ::: "memory"); SBAR();
;     o[0] = __builtin_amdgcn_mfma_f32_32x32x16_bf16(pa, PK(l0, h0), o[0], 0, 0, 0);
;     asm volatile("s_waitcnt lgkmcnt(4)" ::: "memory"); SBAR();
;     o[1] = __builtin_amdgcn_mfma_f32_32x32x16_bf16(pa, PK(l1, h1), o[1], 0, 0, 0);
;     asm volatile("s_waitcnt lgkmcnt(2)" ::: "memory"); SBAR();
;     o[2] = __builtin_amdgcn_mfma_f32_32x32x16_bf16(pa, PK(l2, h2), o[2], 0, 0, 0);
;     asm volatile("s_waitcnt lgkmcnt(0)" ::: "memory"); SBAR();
;     o[3] = __builtin_amdgcn_mfma_f32_32x32x16_bf16(pa, PK(l3, h3), o[3], 0, 0, 0);
;     ...
; }
; __device__ __forceinline__ void pv_d0(f32x16* o, int vb, bf16x8 pa0, bf16x8 pa1, bf16x8 pa2, bf16x8 pa3) {
;     __builtin_amdgcn_s_setprio(1);
;     pv_ks<0>(o, vb, pa0); pv_ks<1>(o, vb, pa1); pv_ks<2>(o, vb, pa2); pv_ks<3>(o, vb, pa3);
;     __builtin_amdgcn_s_setprio(0);
; }
; __device__ __forceinline__ void exp_half(f32x16& p) {
; #pragma unroll
;     for (int r = 0; r < 16; ++r) p[r] = __builtin_amdgcn_exp2f(p[r]);
; }
; __device__ __forceinline__ void pack_p(const f32x16& p0, const f32x16& p1, float& l_reg, bf16x8& pa0, bf16x8& pa1, bf16x8& pa2, bf16x8& pa3) {
;     float ps = 0;
; #pragma unroll
;     for (int r = 0; r < 16; ++r) ps += p0[r];
; #pragma unroll
;     for (int r = 0; r < 16; ++r) ps += p1[r];
;     l_reg += ps;
;     ...
;     PK4(p0, 0, pa0); PK4(p0, 8, pa1); PK4(p1, 0, pa2); PK4(p1, 8, pa3);
;     ...
; }
.Lsym_last3:
	s_waitcnt vmcnt(0)
	s_barrier
	s_waitcnt lgkmcnt(6)
	v_mfma_f32_32x32x16_bf16 v[48:63], v[128:131], v[144:147], v[48:63]
	ds_read_b64_tr_b16 v[144:145], v252 offset:53248
	ds_read_b64_tr_b16 v[146:147], v252 offset:55296
	v_exp_f32_e32 v120, v120
	v_exp_f32_e32 v121, v121
	s_waitcnt lgkmcnt(6)
	v_mfma_f32_32x32x16_bf16 v[32:47], v[128:131], v[148:151], v[32:47]
	ds_read_b64_tr_b16 v[148:149], v252 offset:53760
	ds_read_b64_tr_b16 v[150:151], v252 offset:55808
	v_exp_f32_e32 v122, v122
	v_exp_f32_e32 v123, v123
	v_add_f32_e32 v182, v120, v182
	v_add_f32_e32 v182, v121, v182
	v_cvt_pk_bf16_f32 v132, v120, v121
	s_waitcnt lgkmcnt(6)
	v_mfma_f32_32x32x16_bf16 v[16:31], v[128:131], v[152:155], v[16:31]
	ds_read_b64_tr_b16 v[152:153], v252 offset:54272
	ds_read_b64_tr_b16 v[154:155], v252 offset:56320
	v_exp_f32_e32 v124, v124
	v_exp_f32_e32 v125, v125
	v_add_f32_e32 v182, v122, v182
	v_add_f32_e32 v182, v123, v182
	v_cvt_pk_bf16_f32 v133, v122, v123
	s_waitcnt lgkmcnt(6)
	v_mfma_f32_32x32x16_bf16 v[0:15], v[128:131], v[156:159], v[0:15]
	ds_read_b64_tr_b16 v[156:157], v252 offset:54784
	ds_read_b64_tr_b16 v[158:159], v252 offset:56832
	v_exp_f32_e32 v126, v126
	v_exp_f32_e32 v127, v127
	v_add_f32_e32 v182, v124, v182
	v_add_f32_e32 v182, v125, v182
	v_cvt_pk_bf16_f32 v134, v124, v125
	v_cvt_pk_bf16_f32 v135, v126, v127
	v_add_f32_e32 v182, v126, v182
	v_add_f32_e32 v182, v127, v182
	s_waitcnt lgkmcnt(6)
	v_mfma_f32_32x32x16_bf16 v[48:63], v[132:135], v[144:147], v[48:63]
	ds_read_b64_tr_b16 v[144:145], v252 offset:57344
	ds_read_b64_tr_b16 v[146:147], v252 offset:59392
	v_exp_f32_e32 v96, v96
	v_exp_f32_e32 v97, v97
	s_waitcnt lgkmcnt(6)
	v_mfma_f32_32x32x16_bf16 v[32:47], v[132:135], v[148:151], v[32:47]
	ds_read_b64_tr_b16 v[148:149], v252 offset:57856
	ds_read_b64_tr_b16 v[150:151], v252 offset:59904
	v_exp_f32_e32 v98, v98
	v_exp_f32_e32 v99, v99
	v_add_f32_e32 v182, v96, v182
	v_add_f32_e32 v182, v97, v182
	v_cvt_pk_bf16_f32 v136, v96, v97
	s_waitcnt lgkmcnt(6)
	v_mfma_f32_32x32x16_bf16 v[16:31], v[132:135], v[152:155], v[16:31]
	ds_read_b64_tr_b16 v[152:153], v252 offset:58368
	ds_read_b64_tr_b16 v[154:155], v252 offset:60416
	v_exp_f32_e32 v100, v100
	v_exp_f32_e32 v101, v101
	v_add_f32_e32 v182, v98, v182
	v_add_f32_e32 v182, v99, v182
	v_cvt_pk_bf16_f32 v137, v98, v99
	s_waitcnt lgkmcnt(6)
	v_mfma_f32_32x32x16_bf16 v[0:15], v[132:135], v[156:159], v[0:15]
	ds_read_b64_tr_b16 v[156:157], v252 offset:58880
	ds_read_b64_tr_b16 v[158:159], v252 offset:60928
	v_exp_f32_e32 v102, v102
	v_exp_f32_e32 v103, v103
	v_add_f32_e32 v182, v100, v182
	v_add_f32_e32 v182, v101, v182
	v_cvt_pk_bf16_f32 v138, v100, v101
	v_cvt_pk_bf16_f32 v139, v102, v103
	v_add_f32_e32 v182, v102, v182
	v_add_f32_e32 v182, v103, v182
	s_waitcnt lgkmcnt(6)
	v_mfma_f32_32x32x16_bf16 v[48:63], v[136:139], v[144:147], v[48:63]
	ds_read_b64_tr_b16 v[144:145], v252 offset:61440
	ds_read_b64_tr_b16 v[146:147], v252 offset:63488
	v_exp_f32_e32 v104, v104
	v_exp_f32_e32 v105, v105
	s_waitcnt lgkmcnt(6)
	v_mfma_f32_32x32x16_bf16 v[32:47], v[136:139], v[148:151], v[32:47]
	ds_read_b64_tr_b16 v[148:149], v252 offset:61952
	ds_read_b64_tr_b16 v[150:151], v252 offset:64000
	v_exp_f32_e32 v106, v106
	v_exp_f32_e32 v107, v107
	v_add_f32_e32 v182, v104, v182
	v_add_f32_e32 v182, v105, v182
	v_cvt_pk_bf16_f32 v140, v104, v105
	s_waitcnt lgkmcnt(6)
	v_mfma_f32_32x32x16_bf16 v[16:31], v[136:139], v[152:155], v[16:31]
	ds_read_b64_tr_b16 v[152:153], v252 offset:62464
	ds_read_b64_tr_b16 v[154:155], v252 offset:64512
	v_exp_f32_e32 v108, v108
	v_exp_f32_e32 v109, v109
	v_add_f32_e32 v182, v106, v182
	v_add_f32_e32 v182, v107, v182
	v_cvt_pk_bf16_f32 v141, v106, v107
	s_waitcnt lgkmcnt(6)
	v_mfma_f32_32x32x16_bf16 v[0:15], v[136:139], v[156:159], v[0:15]
	ds_read_b64_tr_b16 v[156:157], v252 offset:62976
	ds_read_b64_tr_b16 v[158:159], v252 offset:65024
	v_exp_f32_e32 v110, v110
	v_exp_f32_e32 v111, v111
	v_add_f32_e32 v182, v108, v182
	v_add_f32_e32 v182, v109, v182
	v_cvt_pk_bf16_f32 v142, v108, v109
	v_cvt_pk_bf16_f32 v143, v110, v111
	v_add_f32_e32 v182, v110, v182
	v_add_f32_e32 v182, v111, v182
	s_waitcnt lgkmcnt(6)
	v_mfma_f32_32x32x16_bf16 v[48:63], v[140:143], v[144:147], v[48:63]
	s_waitcnt lgkmcnt(4)
	v_mfma_f32_32x32x16_bf16 v[32:47], v[140:143], v[148:151], v[32:47]
	s_waitcnt lgkmcnt(2)
	v_mfma_f32_32x32x16_bf16 v[16:31], v[140:143], v[152:155], v[16:31]
	s_waitcnt lgkmcnt(0)
	v_mfma_f32_32x32x16_bf16 v[0:15], v[140:143], v[156:159], v[0:15]
